# non-temporal hint on once-read streaming loads (gates in branch-merge, residual input in out-proj / ffn-out epilogues)
# speedup vs baseline: 1.0184x; 1.0184x over previous
; __device__ __forceinline__ unsigned cvt_pk_bf16(float lo, float hi) { unsigned r; asm volatile("v_cvt_pk_bf16_f32 %0, %1, %2" : "=v"(r) : "v"(lo), "v"(hi)); return r; }
;     __device__ __forceinline__ void operator()(const f32x4 (&acc)[2][2][4][2], const pg8::Unit& u, int wr, int wc, int fr, int fq, LAS unsigned char*) const {
;     ...
;                 const int row = row0 + ai * 128 + m * 16; const size_t off = (size_t)row * DM + col0; float q = 0.f;
; #pragma unroll
;                 for (int bj = 0; bj < 2; ++bj)
; #pragma unroll
;                     for (int n = 0; n < 2; ++n) { const size_t o = off + bj * 128 + n * 16; const f32x4 xv = *(const f32x4*)(xin + o) + acc[ai][bj][m][n]; *(f32x4*)(xout + o) = xv;
;                         q += (xv[0] * xv[0] + xv[1] * xv[1]) + (xv[2] * xv[2] + xv[3] * xv[3]);
;                         u32x2 w; w.x = cvt_pk_bf16(xv[0], xv[1]); w.y = cvt_pk_bf16(xv[2], xv[3]); *(u32x2*)(xb + o) = w; }
;                 q += __shfl_xor(q, 16); q += __shfl_xor(q, 32);
;                 if (fq == 0) ssq[(size_t)row * 16 + u.pn * 4 + wc] = q;
.LBB0_64:
	v_lshl_add_u32 v136, s62, 8, v142
	v_lshl_or_b32 v137, s60, 8, v144
	s_lshl_b32 s26, s60, 4
	s_lshl_b32 s27, s81, 2
	s_add_u32 s26, s26, s27
	v_lshl_add_u32 v139, v136, 10, v137
	v_lshl_add_u32 v140, v136, 6, s26
	v_lshlrev_b32_e32 v138, 2, v139
	v_lshlrev_b32_e32 v139, 1, v139
	v_xor_b32_e32 v141, 16, v187
	v_xor_b32_e32 v172, 32, v187
	v_lshlrev_b32_e32 v141, 2, v141
	v_lshlrev_b32_e32 v172, 2, v172
	global_load_dwordx4 v[198:201], v138, s[18:19] nt
	global_load_dwordx4 v[202:205], v138, s[18:19] offset:64 nt
	global_load_dwordx4 v[206:209], v138, s[18:19] offset:512 nt
	global_load_dwordx4 v[210:213], v138, s[18:19] offset:576 nt
	v_add_u32_e32 v173, 0x10000, v138
	global_load_dwordx4 v[214:217], v173, s[18:19] nt
	global_load_dwordx4 v[218:221], v173, s[18:19] offset:64 nt
	global_load_dwordx4 v[222:225], v173, s[18:19] offset:512 nt
	global_load_dwordx4 v[226:229], v173, s[18:19] offset:576 nt
	v_add_u32_e32 v173, 0x20000, v138
	global_load_dwordx4 v[156:159], v173, s[18:19] nt
	global_load_dwordx4 v[160:163], v173, s[18:19] offset:64 nt
	global_load_dwordx4 v[164:167], v173, s[18:19] offset:512 nt
	global_load_dwordx4 v[168:171], v173, s[18:19] offset:576 nt
	v_mov_b32_e32 v174, v138
	v_mov_b32_e32 v175, v139
	v_mov_b32_e32 v176, v140
	s_waitcnt vmcnt(11)
	v_pk_add_f32 v[200:201], v[128:129], v[200:201]
	v_pk_add_f32 v[198:199], v[126:127], v[198:199]
	global_store_dwordx4 v174, v[198:201], s[12:13]
	v_mul_f32_e32 v178, v201, v201
	v_mul_f32_e32 v177, v199, v199
	v_fmac_f32_e32 v177, v198, v198
	v_fmac_f32_e32 v178, v200, v200
	v_cvt_pk_bf16_f32 v180, v198, v199
	v_cvt_pk_bf16_f32 v181, v200, v201
	v_add_f32_e32 v179, v177, v178
	global_store_dwordx2 v175, v[180:181], s[48:49]
	s_waitcnt vmcnt(12)
	v_pk_add_f32 v[204:205], v[124:125], v[204:205]
	v_pk_add_f32 v[202:203], v[122:123], v[202:203]
	global_store_dwordx4 v174, v[202:205], s[12:13] offset:64
	v_mul_f32_e32 v178, v205, v205
	v_mul_f32_e32 v177, v203, v203
	v_fmac_f32_e32 v177, v202, v202
	v_fmac_f32_e32 v178, v204, v204
	v_cvt_pk_bf16_f32 v182, v202, v203
	v_cvt_pk_bf16_f32 v183, v204, v205
	v_add_f32_e32 v177, v177, v178
	v_add_f32_e32 v179, v179, v177
	global_store_dwordx2 v175, v[182:183], s[48:49] offset:32
	s_waitcnt vmcnt(13)
	v_pk_add_f32 v[208:209], v[120:121], v[208:209]
	v_pk_add_f32 v[206:207], v[118:119], v[206:207]
	global_store_dwordx4 v174, v[206:209], s[12:13] offset:512
	v_mul_f32_e32 v178, v209, v209
	v_mul_f32_e32 v177, v207, v207
	v_fmac_f32_e32 v177, v206, v206
	v_fmac_f32_e32 v178, v208, v208
	v_cvt_pk_bf16_f32 v180, v206, v207
	v_cvt_pk_bf16_f32 v181, v208, v209
	v_add_f32_e32 v177, v177, v178
	v_add_f32_e32 v179, v179, v177
	global_store_dwordx2 v175, v[180:181], s[48:49] offset:256
	s_waitcnt vmcnt(14)
	v_pk_add_f32 v[212:213], v[116:117], v[212:213]
	v_pk_add_f32 v[210:211], v[114:115], v[210:211]
	global_store_dwordx4 v174, v[210:213], s[12:13] offset:576
	v_mul_f32_e32 v178, v213, v213
	v_mul_f32_e32 v177, v211, v211
	v_fmac_f32_e32 v177, v210, v210
	v_fmac_f32_e32 v178, v212, v212
	v_cvt_pk_bf16_f32 v182, v210, v211
	v_cvt_pk_bf16_f32 v183, v212, v213
	v_add_f32_e32 v177, v177, v178
	v_add_f32_e32 v179, v179, v177
	global_store_dwordx2 v175, v[182:183], s[48:49] offset:288
	ds_bpermute_b32 v177, v141, v179
	s_waitcnt lgkmcnt(0)
	v_add_f32_e32 v179, v179, v177
	ds_bpermute_b32 v178, v172, v179
	s_waitcnt lgkmcnt(0)
	v_add_f32_e32 v179, v179, v178
	s_and_saveexec_b64 s[62:63], s[4:5]
	global_store_dword v176, v179, s[14:15]
	s_mov_b64 exec, s[62:63]
	v_add_u32_e32 v173, 0x30000, v138
	global_load_dwordx4 v[198:201], v173, s[18:19] nt
	global_load_dwordx4 v[202:205], v173, s[18:19] offset:64 nt
	global_load_dwordx4 v[206:209], v173, s[18:19] offset:512 nt
	global_load_dwordx4 v[210:213], v173, s[18:19] offset:576 nt
	v_add_u32_e32 v174, 0x10000, v138
	v_add_u32_e32 v175, 0x8000, v139
	v_add_u32_e32 v176, 0x400, v140
	s_waitcnt vmcnt(20)
	v_pk_add_f32 v[216:217], v[112:113], v[216:217]
	v_pk_add_f32 v[214:215], v[110:111], v[214:215]
	global_store_dwordx4 v174, v[214:217], s[12:13]
	v_mul_f32_e32 v178, v217, v217
	v_mul_f32_e32 v177, v215, v215
	v_fmac_f32_e32 v177, v214, v214
	v_fmac_f32_e32 v178, v216, v216
	v_cvt_pk_bf16_f32 v180, v214, v215
	v_cvt_pk_bf16_f32 v181, v216, v217
	v_add_f32_e32 v179, v177, v178
	global_store_dwordx2 v175, v[180:181], s[48:49]
	s_waitcnt vmcnt(21)
	v_pk_add_f32 v[220:221], v[108:109], v[220:221]
	v_pk_add_f32 v[218:219], v[106:107], v[218:219]
	global_store_dwordx4 v174, v[218:221], s[12:13] offset:64
	v_mul_f32_e32 v178, v221, v221
	v_mul_f32_e32 v177, v219, v219
	v_fmac_f32_e32 v177, v218, v218
	v_fmac_f32_e32 v178, v220, v220
	v_cvt_pk_bf16_f32 v182, v218, v219
	v_cvt_pk_bf16_f32 v183, v220, v221
	v_add_f32_e32 v177, v177, v178
	v_add_f32_e32 v179, v179, v177
	global_store_dwordx2 v175, v[182:183], s[48:49] offset:32
	s_waitcnt vmcnt(22)
	v_pk_add_f32 v[224:225], v[104:105], v[224:225]
	v_pk_add_f32 v[222:223], v[102:103], v[222:223]
	global_store_dwordx4 v174, v[222:225], s[12:13] offset:512
	v_mul_f32_e32 v178, v225, v225
	v_mul_f32_e32 v177, v223, v223
	v_fmac_f32_e32 v177, v222, v222
	v_fmac_f32_e32 v178, v224, v224
	v_cvt_pk_bf16_f32 v180, v222, v223
	v_cvt_pk_bf16_f32 v181, v224, v225
	v_add_f32_e32 v177, v177, v178
	v_add_f32_e32 v179, v179, v177
	global_store_dwordx2 v175, v[180:181], s[48:49] offset:256
	s_waitcnt vmcnt(23)
	v_pk_add_f32 v[228:229], v[100:101], v[228:229]
	v_pk_add_f32 v[226:227], v[98:99], v[226:227]
	global_store_dwordx4 v174, v[226:229], s[12:13] offset:576
	v_mul_f32_e32 v178, v229, v229
	v_mul_f32_e32 v177, v227, v227
	v_fmac_f32_e32 v177, v226, v226
	v_fmac_f32_e32 v178, v228, v228
	v_cvt_pk_bf16_f32 v182, v226, v227
	v_cvt_pk_bf16_f32 v183, v228, v229
	v_add_f32_e32 v177, v177, v178
	v_add_f32_e32 v179, v179, v177
	global_store_dwordx2 v175, v[182:183], s[48:49] offset:288
	ds_bpermute_b32 v177, v141, v179
	s_waitcnt lgkmcnt(0)
; __device__ __forceinline__ unsigned cvt_pk_bf16(float lo, float hi) { unsigned r; asm volatile("v_cvt_pk_bf16_f32 %0, %1, %2" : "=v"(r) : "v"(lo), "v"(hi)); return r; }
;     __device__ __forceinline__ void operator()(const f32x4 (&acc)[2][2][4][2], const pg8::Unit& u, int wr, int wc, int fr, int fq, LAS unsigned char*) const {
;     ...
;                 const int row = row0 + ai * 128 + m * 16; const size_t off = (size_t)row * DM + col0; float q = 0.f;
; #pragma unroll
;                 for (int bj = 0; bj < 2; ++bj)
; #pragma unroll
;                     for (int n = 0; n < 2; ++n) { const size_t o = off + bj * 128 + n * 16; const f32x4 xv = *(const f32x4*)(xin + o) + acc[ai][bj][m][n]; *(f32x4*)(xout + o) = xv;
;                         q += (xv[0] * xv[0] + xv[1] * xv[1]) + (xv[2] * xv[2] + xv[3] * xv[3]);
;                         u32x2 w; w.x = cvt_pk_bf16(xv[0], xv[1]); w.y = cvt_pk_bf16(xv[2], xv[3]); *(u32x2*)(xb + o) = w; }
;                 q += __shfl_xor(q, 16); q += __shfl_xor(q, 32);
;                 if (fq == 0) ssq[(size_t)row * 16 + u.pn * 4 + wc] = q;
	v_add_f32_e32 v179, v179, v177
	ds_bpermute_b32 v178, v172, v179
	s_waitcnt lgkmcnt(0)
	v_add_f32_e32 v179, v179, v178
	s_and_saveexec_b64 s[62:63], s[4:5]
	global_store_dword v176, v179, s[14:15]
	s_mov_b64 exec, s[62:63]
	v_add_u32_e32 v173, 0x80000, v138
	global_load_dwordx4 v[214:217], v173, s[18:19] nt
	global_load_dwordx4 v[218:221], v173, s[18:19] offset:64 nt
	global_load_dwordx4 v[222:225], v173, s[18:19] offset:512 nt
	global_load_dwordx4 v[226:229], v173, s[18:19] offset:576 nt
	v_add_u32_e32 v174, 0x20000, v138
	v_add_u32_e32 v175, 0x10000, v139
	v_add_u32_e32 v176, 0x800, v140
	s_waitcnt vmcnt(29)
	v_pk_add_f32 v[158:159], v[96:97], v[158:159]
	v_pk_add_f32 v[156:157], v[94:95], v[156:157]
	global_store_dwordx4 v174, v[156:159], s[12:13]
	v_mul_f32_e32 v178, v159, v159
	v_mul_f32_e32 v177, v157, v157
	v_fmac_f32_e32 v177, v156, v156
	v_fmac_f32_e32 v178, v158, v158
	v_cvt_pk_bf16_f32 v180, v156, v157
	v_cvt_pk_bf16_f32 v181, v158, v159
	v_add_f32_e32 v179, v177, v178
	global_store_dwordx2 v175, v[180:181], s[48:49]
	s_waitcnt vmcnt(30)
	v_pk_add_f32 v[162:163], v[92:93], v[162:163]
	v_pk_add_f32 v[160:161], v[90:91], v[160:161]
	global_store_dwordx4 v174, v[160:163], s[12:13] offset:64
	v_mul_f32_e32 v178, v163, v163
	v_mul_f32_e32 v177, v161, v161
	v_fmac_f32_e32 v177, v160, v160
	v_fmac_f32_e32 v178, v162, v162
	v_cvt_pk_bf16_f32 v182, v160, v161
	v_cvt_pk_bf16_f32 v183, v162, v163
	v_add_f32_e32 v177, v177, v178
	v_add_f32_e32 v179, v179, v177
	global_store_dwordx2 v175, v[182:183], s[48:49] offset:32
	s_waitcnt vmcnt(31)
	v_pk_add_f32 v[166:167], v[88:89], v[166:167]
	v_pk_add_f32 v[164:165], v[86:87], v[164:165]
	global_store_dwordx4 v174, v[164:167], s[12:13] offset:512
	v_mul_f32_e32 v178, v167, v167
	v_mul_f32_e32 v177, v165, v165
	v_fmac_f32_e32 v177, v164, v164
	v_fmac_f32_e32 v178, v166, v166
	v_cvt_pk_bf16_f32 v180, v164, v165
	v_cvt_pk_bf16_f32 v181, v166, v167
	v_add_f32_e32 v177, v177, v178
	v_add_f32_e32 v179, v179, v177
	global_store_dwordx2 v175, v[180:181], s[48:49] offset:256
	s_waitcnt vmcnt(32)
	v_pk_add_f32 v[170:171], v[84:85], v[170:171]
	v_pk_add_f32 v[168:169], v[82:83], v[168:169]
	global_store_dwordx4 v174, v[168:171], s[12:13] offset:576
	v_mul_f32_e32 v178, v171, v171
	v_mul_f32_e32 v177, v169, v169
	v_fmac_f32_e32 v177, v168, v168
	v_fmac_f32_e32 v178, v170, v170
	v_cvt_pk_bf16_f32 v182, v168, v169
	v_cvt_pk_bf16_f32 v183, v170, v171
	v_add_f32_e32 v177, v177, v178
	v_add_f32_e32 v179, v179, v177
	global_store_dwordx2 v175, v[182:183], s[48:49] offset:288
	ds_bpermute_b32 v177, v141, v179
	s_waitcnt lgkmcnt(0)
	v_add_f32_e32 v179, v179, v177
	ds_bpermute_b32 v178, v172, v179
	s_waitcnt lgkmcnt(0)
	v_add_f32_e32 v179, v179, v178
	s_and_saveexec_b64 s[62:63], s[4:5]
	global_store_dword v176, v179, s[14:15]
	s_mov_b64 exec, s[62:63]
	v_add_u32_e32 v173, 0x90000, v138
	global_load_dwordx4 v[156:159], v173, s[18:19] nt
	global_load_dwordx4 v[160:163], v173, s[18:19] offset:64 nt
	global_load_dwordx4 v[164:167], v173, s[18:19] offset:512 nt
	global_load_dwordx4 v[168:171], v173, s[18:19] offset:576 nt
	v_add_u32_e32 v174, 0x30000, v138
	v_add_u32_e32 v175, 0x18000, v139
	v_add_u32_e32 v176, 0xc00, v140
	s_waitcnt vmcnt(29)
	v_pk_add_f32 v[200:201], v[80:81], v[200:201]
	v_pk_add_f32 v[198:199], v[78:79], v[198:199]
	global_store_dwordx4 v174, v[198:201], s[12:13]
	v_mul_f32_e32 v178, v201, v201
	v_mul_f32_e32 v177, v199, v199
	v_fmac_f32_e32 v177, v198, v198
	v_fmac_f32_e32 v178, v200, v200
	v_cvt_pk_bf16_f32 v180, v198, v199
	v_cvt_pk_bf16_f32 v181, v200, v201
	v_add_f32_e32 v179, v177, v178
	global_store_dwordx2 v175, v[180:181], s[48:49]
	s_waitcnt vmcnt(30)
	v_pk_add_f32 v[204:205], v[76:77], v[204:205]
	v_pk_add_f32 v[202:203], v[74:75], v[202:203]
	global_store_dwordx4 v174, v[202:205], s[12:13] offset:64
	v_mul_f32_e32 v178, v205, v205
	v_mul_f32_e32 v177, v203, v203
	v_fmac_f32_e32 v177, v202, v202
	v_fmac_f32_e32 v178, v204, v204
	v_cvt_pk_bf16_f32 v182, v202, v203
	v_cvt_pk_bf16_f32 v183, v204, v205
	v_add_f32_e32 v177, v177, v178
	v_add_f32_e32 v179, v179, v177
	global_store_dwordx2 v175, v[182:183], s[48:49] offset:32
	s_waitcnt vmcnt(31)
	v_pk_add_f32 v[208:209], v[72:73], v[208:209]
	v_pk_add_f32 v[206:207], v[70:71], v[206:207]
	global_store_dwordx4 v174, v[206:209], s[12:13] offset:512
	v_mul_f32_e32 v178, v209, v209
	v_mul_f32_e32 v177, v207, v207
	v_fmac_f32_e32 v177, v206, v206
	v_fmac_f32_e32 v178, v208, v208
	v_cvt_pk_bf16_f32 v180, v206, v207
	v_cvt_pk_bf16_f32 v181, v208, v209
	v_add_f32_e32 v177, v177, v178
	v_add_f32_e32 v179, v179, v177
	global_store_dwordx2 v175, v[180:181], s[48:49] offset:256
	s_waitcnt vmcnt(32)
	v_pk_add_f32 v[212:213], v[68:69], v[212:213]
	v_pk_add_f32 v[210:211], v[66:67], v[210:211]
	global_store_dwordx4 v174, v[210:213], s[12:13] offset:576
	v_mul_f32_e32 v178, v213, v213
	v_mul_f32_e32 v177, v211, v211
	v_fmac_f32_e32 v177, v210, v210
	v_fmac_f32_e32 v178, v212, v212
	v_cvt_pk_bf16_f32 v182, v210, v211
	v_cvt_pk_bf16_f32 v183, v212, v213
	v_add_f32_e32 v177, v177, v178
	v_add_f32_e32 v179, v179, v177
	global_store_dwordx2 v175, v[182:183], s[48:49] offset:288
	ds_bpermute_b32 v177, v141, v179
	s_waitcnt lgkmcnt(0)
	v_add_f32_e32 v179, v179, v177
	ds_bpermute_b32 v178, v172, v179
	s_waitcnt lgkmcnt(0)
	v_add_f32_e32 v179, v179, v178
	s_and_saveexec_b64 s[62:63], s[4:5]
	global_store_dword v176, v179, s[14:15]
	s_mov_b64 exec, s[62:63]
	v_add_u32_e32 v173, 0xa0000, v138
	global_load_dwordx4 v[198:201], v173, s[18:19] nt
	global_load_dwordx4 v[202:205], v173, s[18:19] offset:64 nt
	global_load_dwordx4 v[206:209], v173, s[18:19] offset:512 nt
	global_load_dwordx4 v[210:213], v173, s[18:19] offset:576 nt
	v_add_u32_e32 v174, 0x80000, v138
	v_add_u32_e32 v175, 0x40000, v139
	v_add_u32_e32 v176, 0x2000, v140
	s_waitcnt vmcnt(29)
; __device__ __forceinline__ unsigned cvt_pk_bf16(float lo, float hi) { unsigned r; asm volatile("v_cvt_pk_bf16_f32 %0, %1, %2" : "=v"(r) : "v"(lo), "v"(hi)); return r; }
;     __device__ __forceinline__ void operator()(const f32x4 (&acc)[2][2][4][2], const pg8::Unit& u, int wr, int wc, int fr, int fq, LAS unsigned char*) const {
;     ...
;                 const int row = row0 + ai * 128 + m * 16; const size_t off = (size_t)row * DM + col0; float q = 0.f;
; #pragma unroll
;                 for (int bj = 0; bj < 2; ++bj)
; #pragma unroll
;                     for (int n = 0; n < 2; ++n) { const size_t o = off + bj * 128 + n * 16; const f32x4 xv = *(const f32x4*)(xin + o) + acc[ai][bj][m][n]; *(f32x4*)(xout + o) = xv;
;                         q += (xv[0] * xv[0] + xv[1] * xv[1]) + (xv[2] * xv[2] + xv[3] * xv[3]);
;                         u32x2 w; w.x = cvt_pk_bf16(xv[0], xv[1]); w.y = cvt_pk_bf16(xv[2], xv[3]); *(u32x2*)(xb + o) = w; }
;                 q += __shfl_xor(q, 16); q += __shfl_xor(q, 32);
;                 if (fq == 0) ssq[(size_t)row * 16 + u.pn * 4 + wc] = q;
	v_pk_add_f32 v[216:217], v[64:65], v[216:217]
	v_pk_add_f32 v[214:215], v[62:63], v[214:215]
	global_store_dwordx4 v174, v[214:217], s[12:13]
	v_mul_f32_e32 v178, v217, v217
	v_mul_f32_e32 v177, v215, v215
	v_fmac_f32_e32 v177, v214, v214
	v_fmac_f32_e32 v178, v216, v216
	v_cvt_pk_bf16_f32 v180, v214, v215
	v_cvt_pk_bf16_f32 v181, v216, v217
	v_add_f32_e32 v179, v177, v178
	global_store_dwordx2 v175, v[180:181], s[48:49]
	s_waitcnt vmcnt(30)
	v_pk_add_f32 v[220:221], v[60:61], v[220:221]
	v_pk_add_f32 v[218:219], v[58:59], v[218:219]
	global_store_dwordx4 v174, v[218:221], s[12:13] offset:64
	v_mul_f32_e32 v178, v221, v221
	v_mul_f32_e32 v177, v219, v219
	v_fmac_f32_e32 v177, v218, v218
	v_fmac_f32_e32 v178, v220, v220
	v_cvt_pk_bf16_f32 v182, v218, v219
	v_cvt_pk_bf16_f32 v183, v220, v221
	v_add_f32_e32 v177, v177, v178
	v_add_f32_e32 v179, v179, v177
	global_store_dwordx2 v175, v[182:183], s[48:49] offset:32
	s_waitcnt vmcnt(31)
	v_pk_add_f32 v[224:225], v[56:57], v[224:225]
	v_pk_add_f32 v[222:223], v[54:55], v[222:223]
	global_store_dwordx4 v174, v[222:225], s[12:13] offset:512
	v_mul_f32_e32 v178, v225, v225
	v_mul_f32_e32 v177, v223, v223
	v_fmac_f32_e32 v177, v222, v222
	v_fmac_f32_e32 v178, v224, v224
	v_cvt_pk_bf16_f32 v180, v222, v223
	v_cvt_pk_bf16_f32 v181, v224, v225
	v_add_f32_e32 v177, v177, v178
	v_add_f32_e32 v179, v179, v177
	global_store_dwordx2 v175, v[180:181], s[48:49] offset:256
	s_waitcnt vmcnt(32)
	v_pk_add_f32 v[228:229], v[52:53], v[228:229]
	v_pk_add_f32 v[226:227], v[50:51], v[226:227]
	global_store_dwordx4 v174, v[226:229], s[12:13] offset:576
	v_mul_f32_e32 v178, v229, v229
	v_mul_f32_e32 v177, v227, v227
	v_fmac_f32_e32 v177, v226, v226
	v_fmac_f32_e32 v178, v228, v228
	v_cvt_pk_bf16_f32 v182, v226, v227
	v_cvt_pk_bf16_f32 v183, v228, v229
	v_add_f32_e32 v177, v177, v178
	v_add_f32_e32 v179, v179, v177
	global_store_dwordx2 v175, v[182:183], s[48:49] offset:288
	ds_bpermute_b32 v177, v141, v179
	s_waitcnt lgkmcnt(0)
	v_add_f32_e32 v179, v179, v177
	ds_bpermute_b32 v178, v172, v179
	s_waitcnt lgkmcnt(0)
	v_add_f32_e32 v179, v179, v178
	s_and_saveexec_b64 s[62:63], s[4:5]
	global_store_dword v176, v179, s[14:15]
	s_mov_b64 exec, s[62:63]
	v_add_u32_e32 v173, 0xb0000, v138
	global_load_dwordx4 v[214:217], v173, s[18:19] nt
	global_load_dwordx4 v[218:221], v173, s[18:19] offset:64 nt
	global_load_dwordx4 v[222:225], v173, s[18:19] offset:512 nt
	global_load_dwordx4 v[226:229], v173, s[18:19] offset:576 nt
	v_add_u32_e32 v174, 0x90000, v138
	v_add_u32_e32 v175, 0x48000, v139
	v_add_u32_e32 v176, 0x2400, v140
	s_waitcnt vmcnt(29)
	v_pk_add_f32 v[158:159], v[48:49], v[158:159]
	v_pk_add_f32 v[156:157], v[46:47], v[156:157]
	global_store_dwordx4 v174, v[156:159], s[12:13]
	v_mul_f32_e32 v178, v159, v159
	v_mul_f32_e32 v177, v157, v157
	v_fmac_f32_e32 v177, v156, v156
	v_fmac_f32_e32 v178, v158, v158
	v_cvt_pk_bf16_f32 v180, v156, v157
	v_cvt_pk_bf16_f32 v181, v158, v159
	v_add_f32_e32 v179, v177, v178
	global_store_dwordx2 v175, v[180:181], s[48:49]
	s_waitcnt vmcnt(30)
	v_pk_add_f32 v[162:163], v[44:45], v[162:163]
	v_pk_add_f32 v[160:161], v[42:43], v[160:161]
	global_store_dwordx4 v174, v[160:163], s[12:13] offset:64
	v_mul_f32_e32 v178, v163, v163
	v_mul_f32_e32 v177, v161, v161
	v_fmac_f32_e32 v177, v160, v160
	v_fmac_f32_e32 v178, v162, v162
	v_cvt_pk_bf16_f32 v182, v160, v161
	v_cvt_pk_bf16_f32 v183, v162, v163
	v_add_f32_e32 v177, v177, v178
	v_add_f32_e32 v179, v179, v177
	global_store_dwordx2 v175, v[182:183], s[48:49] offset:32
	s_waitcnt vmcnt(31)
	v_pk_add_f32 v[166:167], v[40:41], v[166:167]
	v_pk_add_f32 v[164:165], v[38:39], v[164:165]
	global_store_dwordx4 v174, v[164:167], s[12:13] offset:512
	v_mul_f32_e32 v178, v167, v167
	v_mul_f32_e32 v177, v165, v165
	v_fmac_f32_e32 v177, v164, v164
	v_fmac_f32_e32 v178, v166, v166
	v_cvt_pk_bf16_f32 v180, v164, v165
	v_cvt_pk_bf16_f32 v181, v166, v167
	v_add_f32_e32 v177, v177, v178
	v_add_f32_e32 v179, v179, v177
	global_store_dwordx2 v175, v[180:181], s[48:49] offset:256
	s_waitcnt vmcnt(32)
	v_pk_add_f32 v[170:171], v[36:37], v[170:171]
	v_pk_add_f32 v[168:169], v[34:35], v[168:169]
	global_store_dwordx4 v174, v[168:171], s[12:13] offset:576
	v_mul_f32_e32 v178, v171, v171
	v_mul_f32_e32 v177, v169, v169
	v_fmac_f32_e32 v177, v168, v168
	v_fmac_f32_e32 v178, v170, v170
	v_cvt_pk_bf16_f32 v182, v168, v169
	v_cvt_pk_bf16_f32 v183, v170, v171
	v_add_f32_e32 v177, v177, v178
	v_add_f32_e32 v179, v179, v177
	global_store_dwordx2 v175, v[182:183], s[48:49] offset:288
	ds_bpermute_b32 v177, v141, v179
	s_waitcnt lgkmcnt(0)
	v_add_f32_e32 v179, v179, v177
	ds_bpermute_b32 v178, v172, v179
	s_waitcnt lgkmcnt(0)
	v_add_f32_e32 v179, v179, v178
	s_and_saveexec_b64 s[62:63], s[4:5]
	global_store_dword v176, v179, s[14:15]
	s_mov_b64 exec, s[62:63]
	v_add_u32_e32 v174, 0xa0000, v138
	v_add_u32_e32 v175, 0x50000, v139
	v_add_u32_e32 v176, 0x2800, v140
	s_waitcnt vmcnt(25)
; __device__ __forceinline__ unsigned cvt_pk_bf16(float lo, float hi) { unsigned r; asm volatile("v_cvt_pk_bf16_f32 %0, %1, %2" : "=v"(r) : "v"(lo), "v"(hi)); return r; }
;     __device__ __forceinline__ void operator()(const f32x4 (&acc)[2][2][4][2], const pg8::Unit& u, int wr, int wc, int fr, int fq, LAS unsigned char*) const {
;     ...
;                 const int row = row0 + ai * 128 + m * 16; const size_t off = (size_t)row * DM + col0; float q = 0.f;
; #pragma unroll
;                 for (int bj = 0; bj < 2; ++bj)
; #pragma unroll
;                     for (int n = 0; n < 2; ++n) { const size_t o = off + bj * 128 + n * 16; const f32x4 xv = *(const f32x4*)(xin + o) + acc[ai][bj][m][n]; *(f32x4*)(xout + o) = xv;
;                         q += (xv[0] * xv[0] + xv[1] * xv[1]) + (xv[2] * xv[2] + xv[3] * xv[3]);
;                         u32x2 w; w.x = cvt_pk_bf16(xv[0], xv[1]); w.y = cvt_pk_bf16(xv[2], xv[3]); *(u32x2*)(xb + o) = w; }
;                 q += __shfl_xor(q, 16); q += __shfl_xor(q, 32);
;                 if (fq == 0) ssq[(size_t)row * 16 + u.pn * 4 + wc] = q;
	v_pk_add_f32 v[200:201], v[32:33], v[200:201]
	v_pk_add_f32 v[198:199], v[30:31], v[198:199]
	global_store_dwordx4 v174, v[198:201], s[12:13]
	v_mul_f32_e32 v178, v201, v201
	v_mul_f32_e32 v177, v199, v199
	v_fmac_f32_e32 v177, v198, v198
	v_fmac_f32_e32 v178, v200, v200
	v_cvt_pk_bf16_f32 v180, v198, v199
	v_cvt_pk_bf16_f32 v181, v200, v201
	v_add_f32_e32 v179, v177, v178
	global_store_dwordx2 v175, v[180:181], s[48:49]
	s_waitcnt vmcnt(26)
	v_pk_add_f32 v[204:205], v[28:29], v[204:205]
	v_pk_add_f32 v[202:203], v[26:27], v[202:203]
	global_store_dwordx4 v174, v[202:205], s[12:13] offset:64
	v_mul_f32_e32 v178, v205, v205
	v_mul_f32_e32 v177, v203, v203
	v_fmac_f32_e32 v177, v202, v202
	v_fmac_f32_e32 v178, v204, v204
	v_cvt_pk_bf16_f32 v182, v202, v203
	v_cvt_pk_bf16_f32 v183, v204, v205
	v_add_f32_e32 v177, v177, v178
	v_add_f32_e32 v179, v179, v177
	global_store_dwordx2 v175, v[182:183], s[48:49] offset:32
	s_waitcnt vmcnt(27)
	v_pk_add_f32 v[208:209], v[24:25], v[208:209]
	v_pk_add_f32 v[206:207], v[22:23], v[206:207]
	global_store_dwordx4 v174, v[206:209], s[12:13] offset:512
	v_mul_f32_e32 v178, v209, v209
	v_mul_f32_e32 v177, v207, v207
	v_fmac_f32_e32 v177, v206, v206
	v_fmac_f32_e32 v178, v208, v208
	v_cvt_pk_bf16_f32 v180, v206, v207
	v_cvt_pk_bf16_f32 v181, v208, v209
	v_add_f32_e32 v177, v177, v178
	v_add_f32_e32 v179, v179, v177
	global_store_dwordx2 v175, v[180:181], s[48:49] offset:256
	s_waitcnt vmcnt(28)
	v_pk_add_f32 v[212:213], v[20:21], v[212:213]
	v_pk_add_f32 v[210:211], v[18:19], v[210:211]
	global_store_dwordx4 v174, v[210:213], s[12:13] offset:576
	v_mul_f32_e32 v178, v213, v213
	v_mul_f32_e32 v177, v211, v211
	v_fmac_f32_e32 v177, v210, v210
	v_fmac_f32_e32 v178, v212, v212
	v_cvt_pk_bf16_f32 v182, v210, v211
	v_cvt_pk_bf16_f32 v183, v212, v213
	v_add_f32_e32 v177, v177, v178
	v_add_f32_e32 v179, v179, v177
	global_store_dwordx2 v175, v[182:183], s[48:49] offset:288
	ds_bpermute_b32 v177, v141, v179
	s_waitcnt lgkmcnt(0)
	v_add_f32_e32 v179, v179, v177
	ds_bpermute_b32 v178, v172, v179
	s_waitcnt lgkmcnt(0)
	v_add_f32_e32 v179, v179, v178
	s_and_saveexec_b64 s[62:63], s[4:5]
	global_store_dword v176, v179, s[14:15]
	s_mov_b64 exec, s[62:63]
	v_add_u32_e32 v174, 0xb0000, v138
	v_add_u32_e32 v175, 0x58000, v139
	v_add_u32_e32 v176, 0x2c00, v140
	s_waitcnt vmcnt(21)
	v_pk_add_f32 v[216:217], v[16:17], v[216:217]
	v_pk_add_f32 v[214:215], v[14:15], v[214:215]
	global_store_dwordx4 v174, v[214:217], s[12:13]
	v_mul_f32_e32 v178, v217, v217
	v_mul_f32_e32 v177, v215, v215
	v_fmac_f32_e32 v177, v214, v214
	v_fmac_f32_e32 v178, v216, v216
	v_cvt_pk_bf16_f32 v180, v214, v215
	v_cvt_pk_bf16_f32 v181, v216, v217
	v_add_f32_e32 v179, v177, v178
	global_store_dwordx2 v175, v[180:181], s[48:49]
	s_waitcnt vmcnt(22)
	v_pk_add_f32 v[220:221], v[12:13], v[220:221]
	v_pk_add_f32 v[218:219], v[10:11], v[218:219]
	global_store_dwordx4 v174, v[218:221], s[12:13] offset:64
	v_mul_f32_e32 v178, v221, v221
	v_mul_f32_e32 v177, v219, v219
	v_fmac_f32_e32 v177, v218, v218
	v_fmac_f32_e32 v178, v220, v220
	v_cvt_pk_bf16_f32 v182, v218, v219
	v_cvt_pk_bf16_f32 v183, v220, v221
	v_add_f32_e32 v177, v177, v178
	v_add_f32_e32 v179, v179, v177
	global_store_dwordx2 v175, v[182:183], s[48:49] offset:32
	s_waitcnt vmcnt(23)
	v_pk_add_f32 v[224:225], v[8:9], v[224:225]
	v_pk_add_f32 v[222:223], v[6:7], v[222:223]
	global_store_dwordx4 v174, v[222:225], s[12:13] offset:512
	v_mul_f32_e32 v178, v225, v225
	v_mul_f32_e32 v177, v223, v223
	v_fmac_f32_e32 v177, v222, v222
	v_fmac_f32_e32 v178, v224, v224
	v_cvt_pk_bf16_f32 v180, v222, v223
	v_cvt_pk_bf16_f32 v181, v224, v225
	v_add_f32_e32 v177, v177, v178
	v_add_f32_e32 v179, v179, v177
	global_store_dwordx2 v175, v[180:181], s[48:49] offset:256
	s_waitcnt vmcnt(24)
	v_pk_add_f32 v[228:229], v[4:5], v[228:229]
	v_pk_add_f32 v[226:227], v[2:3], v[226:227]
	global_store_dwordx4 v174, v[226:229], s[12:13] offset:576
	v_mul_f32_e32 v178, v229, v229
	v_mul_f32_e32 v177, v227, v227
	v_fmac_f32_e32 v177, v226, v226
	v_fmac_f32_e32 v178, v228, v228
	v_cvt_pk_bf16_f32 v182, v226, v227
	v_cvt_pk_bf16_f32 v183, v228, v229
	v_add_f32_e32 v177, v177, v178
	v_add_f32_e32 v179, v179, v177
	global_store_dwordx2 v175, v[182:183], s[48:49] offset:288
	ds_bpermute_b32 v177, v141, v179
	s_waitcnt lgkmcnt(0)
	v_add_f32_e32 v179, v179, v177
	ds_bpermute_b32 v178, v172, v179
	s_waitcnt lgkmcnt(0)
	v_add_f32_e32 v179, v179, v178
	s_and_saveexec_b64 s[62:63], s[4:5]
	global_store_dword v176, v179, s[14:15]
	s_mov_b64 exec, s[62:63]
	s_andn2_b64 vcc, exec, s[6:7]
	s_mov_b64 s[6:7], -1
	s_cbranch_vccnz .LBB0_53
	s_andn2_b64 vcc, exec, s[22:23]
	s_cbranch_vccnz .LBB0_52
	s_barrier
	s_branch .LBB0_52

; __device__ __forceinline__ float bflo(unsigned w) { return __uint_as_float(w << 16); }
; __device__ __forceinline__ float bfhi(unsigned w) { return __uint_as_float(w & 0xffff0000u); }
;     __device__ __forceinline__ void mid(f32x4 (&acc)[2][2][4][2], const pg8::Unit& u, int seg, int wr, int wc, int fr, int fq) const {
;     ...
;                 const bf16_t* gp = gates + (size_t)(row0 + ai * 128 + m * 16) * 3072 + seg * 1024 + col0;
; #pragma unroll
;                 for (int bj = 0; bj < 2; ++bj) {
;                     const u32x4 gw = *(const u32x4*)(gp + bj * 128), hw = *(const u32x4*)(gp + 1024 + bj * 128);
;                     f32x4 v0 = acc[ai][bj][m][0], v1 = acc[ai][bj][m][1];
;                     v0[0] *= bflo(gw.x) * __builtin_amdgcn_rcpf(fmaxf(bflo(hw.x), 1e-20f)); v0[1] *= bfhi(gw.x) * __builtin_amdgcn_rcpf(fmaxf(bfhi(hw.x), 1e-20f));
;                     v0[2] *= bflo(gw.y) * __builtin_amdgcn_rcpf(fmaxf(bflo(hw.y), 1e-20f)); v0[3] *= bfhi(gw.y) * __builtin_amdgcn_rcpf(fmaxf(bfhi(hw.y), 1e-20f));
;                     v1[0] *= bflo(gw.z) * __builtin_amdgcn_rcpf(fmaxf(bflo(hw.z), 1e-20f)); v1[1] *= bfhi(gw.z) * __builtin_amdgcn_rcpf(fmaxf(bfhi(hw.z), 1e-20f));
;                     v1[2] *= bflo(gw.w) * __builtin_amdgcn_rcpf(fmaxf(bflo(hw.w), 1e-20f)); v1[3] *= bfhi(gw.w) * __builtin_amdgcn_rcpf(fmaxf(bfhi(hw.w), 1e-20f));
;                     acc[ai][bj][m][0] = v0; acc[ai][bj][m][1] = v1;
.LBB0_111:
	v_mov_b32_e32 v130, v165
	v_mov_b32_e32 v131, v164
	s_cmpk_eq_i32 s56, 0x400
	v_lshl_add_u32 v130, v130, 3, s88
	v_add_u32_e32 v170, s89, v131
	v_mov_b64_e32 v[134:135], s[12:13]
	s_cselect_b32 s28, 0, 0x800
	v_ashrrev_i32_e32 v131, 31, v130
	v_mad_i64_i32 v[132:133], s[26:27], v170, s82, v[134:135]
	v_lshl_add_u64 v[132:133], v[132:133], 0, s[28:29]
	v_lshlrev_b64 v[136:137], 1, v[130:131]
	v_lshl_add_u64 v[162:163], v[132:133], 0, v[136:137]
	global_load_dwordx4 v[130:133], v[162:163], off nt
	global_load_dwordx4 v[172:175], v[162:163], off offset:2048 nt
	s_waitcnt vmcnt(0)
	v_lshlrev_b32_e32 v178, 16, v130
	v_lshlrev_b32_e32 v171, 16, v172
	v_and_b32_e32 v179, 0xffff0000, v130
	v_lshlrev_b32_e32 v130, 16, v173
	v_max_f32_e32 v171, v171, v171
	v_max_f32_e32 v130, v130, v130
	v_max_f32_e32 v171, 0x1e3ce508, v171
	v_max_f32_e32 v130, 0x1e3ce508, v130
	v_rcp_f32_e32 v176, v171
	v_and_b32_e32 v171, 0xffff0000, v172
	v_rcp_f32_e32 v172, v130
	v_and_b32_e32 v130, 0xffff0000, v173
	v_max_f32_e32 v130, v130, v130
	v_max_f32_e32 v130, 0x1e3ce508, v130
	v_rcp_f32_e32 v173, v130
	v_lshlrev_b32_e32 v130, 16, v131
	v_and_b32_e32 v131, 0xffff0000, v131
	v_max_f32_e32 v171, v171, v171
	v_pk_mul_f32 v[130:131], v[172:173], v[130:131]
	v_lshlrev_b32_e32 v172, 16, v132
	v_pk_mul_f32 v[128:129], v[128:129], v[130:131]
	v_lshlrev_b32_e32 v130, 16, v174
	v_and_b32_e32 v131, 0xffff0000, v174
	v_max_f32_e32 v130, v130, v130
	v_max_f32_e32 v131, v131, v131
	v_max_f32_e32 v130, 0x1e3ce508, v130
	v_max_f32_e32 v131, 0x1e3ce508, v131
	v_rcp_f32_e32 v130, v130
	v_rcp_f32_e32 v131, v131
	v_and_b32_e32 v173, 0xffff0000, v132
	v_lshlrev_b32_e32 v132, 16, v133
	v_and_b32_e32 v133, 0xffff0000, v133
	v_pk_mul_f32 v[130:131], v[130:131], v[172:173]
	v_max_f32_e32 v171, 0x1e3ce508, v171
	v_pk_mul_f32 v[122:123], v[122:123], v[130:131]
	v_lshlrev_b32_e32 v130, 16, v175
	v_and_b32_e32 v131, 0xffff0000, v175
	v_max_f32_e32 v130, v130, v130
	v_max_f32_e32 v131, v131, v131
	v_max_f32_e32 v130, 0x1e3ce508, v130
	v_max_f32_e32 v131, 0x1e3ce508, v131
	v_rcp_f32_e32 v130, v130
	v_rcp_f32_e32 v131, v131
	v_rcp_f32_e32 v177, v171
	v_pk_mul_f32 v[130:131], v[130:131], v[132:133]
	s_nop 0
	v_pk_mul_f32 v[124:125], v[124:125], v[130:131]
	global_load_dwordx4 v[130:133], v[162:163], off offset:256 nt
	global_load_dwordx4 v[172:175], v[162:163], off offset:2304 nt
	v_pk_mul_f32 v[176:177], v[176:177], v[178:179]
	s_waitcnt vmcnt(0)
	v_lshlrev_b32_e32 v162, 16, v172
	v_and_b32_e32 v163, 0xffff0000, v172
	v_max_f32_e32 v162, v162, v162
	v_max_f32_e32 v163, v163, v163
	v_max_f32_e32 v162, 0x1e3ce508, v162
	v_max_f32_e32 v163, 0x1e3ce508, v163
	v_rcp_f32_e32 v162, v162
	v_rcp_f32_e32 v163, v163
	v_pk_mul_f32 v[126:127], v[126:127], v[176:177]
	v_lshlrev_b32_e32 v176, 16, v130
	v_and_b32_e32 v177, 0xffff0000, v130
	v_lshlrev_b32_e32 v130, 16, v173
	v_max_f32_e32 v130, v130, v130
	v_pk_mul_f32 v[162:163], v[162:163], v[176:177]
	v_max_f32_e32 v130, 0x1e3ce508, v130
	v_pk_mul_f32 v[118:119], v[118:119], v[162:163]
	v_rcp_f32_e32 v162, v130
	v_and_b32_e32 v130, 0xffff0000, v173
	v_max_f32_e32 v130, v130, v130
	v_max_f32_e32 v130, 0x1e3ce508, v130
	v_rcp_f32_e32 v163, v130
	v_lshlrev_b32_e32 v130, 16, v131
	v_and_b32_e32 v131, 0xffff0000, v131
	v_pk_mul_f32 v[130:131], v[162:163], v[130:131]
	s_nop 0
	v_pk_mul_f32 v[120:121], v[120:121], v[130:131]
	v_lshlrev_b32_e32 v130, 16, v174
	v_and_b32_e32 v131, 0xffff0000, v174
	v_max_f32_e32 v130, v130, v130
	v_max_f32_e32 v131, v131, v131
	v_max_f32_e32 v130, 0x1e3ce508, v130
	v_max_f32_e32 v131, 0x1e3ce508, v131
	v_rcp_f32_e32 v130, v130
	v_rcp_f32_e32 v131, v131
	v_lshlrev_b32_e32 v162, 16, v132
	v_and_b32_e32 v163, 0xffff0000, v132
	v_lshlrev_b32_e32 v132, 16, v133
	v_pk_mul_f32 v[130:131], v[130:131], v[162:163]
	v_and_b32_e32 v133, 0xffff0000, v133
	v_pk_mul_f32 v[114:115], v[114:115], v[130:131]
	v_lshlrev_b32_e32 v130, 16, v175
	v_and_b32_e32 v131, 0xffff0000, v175
	v_max_f32_e32 v130, v130, v130
	v_max_f32_e32 v131, v131, v131
	v_max_f32_e32 v130, 0x1e3ce508, v130
	v_max_f32_e32 v131, 0x1e3ce508, v131
	v_rcp_f32_e32 v130, v130
	v_rcp_f32_e32 v131, v131
	s_nop 0
	v_pk_mul_f32 v[130:131], v[130:131], v[132:133]
	s_nop 0
	v_pk_mul_f32 v[116:117], v[116:117], v[130:131]
	v_add_u32_e32 v130, 16, v170
	v_mad_i64_i32 v[130:131], s[26:27], v130, s82, v[134:135]
	v_lshl_add_u64 v[130:131], v[130:131], 0, s[28:29]
	v_lshl_add_u64 v[162:163], v[130:131], 0, v[136:137]
	global_load_dwordx4 v[130:133], v[162:163], off nt
	global_load_dwordx4 v[172:175], v[162:163], off offset:2048 nt
	s_waitcnt vmcnt(0)
	v_lshlrev_b32_e32 v178, 16, v130
	v_lshlrev_b32_e32 v171, 16, v172
	v_and_b32_e32 v179, 0xffff0000, v130
	v_lshlrev_b32_e32 v130, 16, v173
	v_max_f32_e32 v171, v171, v171
	v_max_f32_e32 v130, v130, v130
	v_max_f32_e32 v171, 0x1e3ce508, v171
	v_max_f32_e32 v130, 0x1e3ce508, v130
	v_rcp_f32_e32 v176, v171
	v_and_b32_e32 v171, 0xffff0000, v172
	v_rcp_f32_e32 v172, v130
	v_and_b32_e32 v130, 0xffff0000, v173
	v_max_f32_e32 v130, v130, v130
	v_max_f32_e32 v130, 0x1e3ce508, v130
	v_rcp_f32_e32 v173, v130
	v_lshlrev_b32_e32 v130, 16, v131
	v_and_b32_e32 v131, 0xffff0000, v131
	v_max_f32_e32 v171, v171, v171
	v_pk_mul_f32 v[130:131], v[172:173], v[130:131]
	v_lshlrev_b32_e32 v172, 16, v132
	v_pk_mul_f32 v[112:113], v[112:113], v[130:131]
	v_lshlrev_b32_e32 v130, 16, v174
	v_and_b32_e32 v131, 0xffff0000, v174
	v_max_f32_e32 v130, v130, v130
	v_max_f32_e32 v131, v131, v131
	v_max_f32_e32 v130, 0x1e3ce508, v130
	v_max_f32_e32 v131, 0x1e3ce508, v131
	v_rcp_f32_e32 v130, v130
	v_rcp_f32_e32 v131, v131
	v_and_b32_e32 v173, 0xffff0000, v132
	v_lshlrev_b32_e32 v132, 16, v133
	v_and_b32_e32 v133, 0xffff0000, v133
	v_pk_mul_f32 v[130:131], v[130:131], v[172:173]
	v_max_f32_e32 v171, 0x1e3ce508, v171
	v_pk_mul_f32 v[106:107], v[106:107], v[130:131]
	v_lshlrev_b32_e32 v130, 16, v175
	v_and_b32_e32 v131, 0xffff0000, v175
	v_max_f32_e32 v130, v130, v130
	v_max_f32_e32 v131, v131, v131
	v_max_f32_e32 v130, 0x1e3ce508, v130
	v_max_f32_e32 v131, 0x1e3ce508, v131
	v_rcp_f32_e32 v130, v130
	v_rcp_f32_e32 v131, v131
	v_rcp_f32_e32 v177, v171
	v_pk_mul_f32 v[130:131], v[130:131], v[132:133]
	s_nop 0
	v_pk_mul_f32 v[108:109], v[108:109], v[130:131]
	global_load_dwordx4 v[130:133], v[162:163], off offset:256 nt
	global_load_dwordx4 v[172:175], v[162:163], off offset:2304 nt
	v_pk_mul_f32 v[176:177], v[176:177], v[178:179]
	s_waitcnt vmcnt(0)
; __device__ __forceinline__ float bflo(unsigned w) { return __uint_as_float(w << 16); }
; __device__ __forceinline__ float bfhi(unsigned w) { return __uint_as_float(w & 0xffff0000u); }
;     __device__ __forceinline__ void mid(f32x4 (&acc)[2][2][4][2], const pg8::Unit& u, int seg, int wr, int wc, int fr, int fq) const {
;     ...
;                 const bf16_t* gp = gates + (size_t)(row0 + ai * 128 + m * 16) * 3072 + seg * 1024 + col0;
; #pragma unroll
;                 for (int bj = 0; bj < 2; ++bj) {
;                     const u32x4 gw = *(const u32x4*)(gp + bj * 128), hw = *(const u32x4*)(gp + 1024 + bj * 128);
;                     f32x4 v0 = acc[ai][bj][m][0], v1 = acc[ai][bj][m][1];
;                     v0[0] *= bflo(gw.x) * __builtin_amdgcn_rcpf(fmaxf(bflo(hw.x), 1e-20f)); v0[1] *= bfhi(gw.x) * __builtin_amdgcn_rcpf(fmaxf(bfhi(hw.x), 1e-20f));
;                     v0[2] *= bflo(gw.y) * __builtin_amdgcn_rcpf(fmaxf(bflo(hw.y), 1e-20f)); v0[3] *= bfhi(gw.y) * __builtin_amdgcn_rcpf(fmaxf(bfhi(hw.y), 1e-20f));
;                     v1[0] *= bflo(gw.z) * __builtin_amdgcn_rcpf(fmaxf(bflo(hw.z), 1e-20f)); v1[1] *= bfhi(gw.z) * __builtin_amdgcn_rcpf(fmaxf(bfhi(hw.z), 1e-20f));
;                     v1[2] *= bflo(gw.w) * __builtin_amdgcn_rcpf(fmaxf(bflo(hw.w), 1e-20f)); v1[3] *= bfhi(gw.w) * __builtin_amdgcn_rcpf(fmaxf(bfhi(hw.w), 1e-20f));
;                     acc[ai][bj][m][0] = v0; acc[ai][bj][m][1] = v1;
	v_lshlrev_b32_e32 v162, 16, v172
	v_and_b32_e32 v163, 0xffff0000, v172
	v_max_f32_e32 v162, v162, v162
	v_max_f32_e32 v163, v163, v163
	v_max_f32_e32 v162, 0x1e3ce508, v162
	v_max_f32_e32 v163, 0x1e3ce508, v163
	v_rcp_f32_e32 v162, v162
	v_rcp_f32_e32 v163, v163
	v_pk_mul_f32 v[110:111], v[110:111], v[176:177]
	v_lshlrev_b32_e32 v176, 16, v130
	v_and_b32_e32 v177, 0xffff0000, v130
	v_lshlrev_b32_e32 v130, 16, v173
	v_max_f32_e32 v130, v130, v130
	v_pk_mul_f32 v[162:163], v[162:163], v[176:177]
	v_max_f32_e32 v130, 0x1e3ce508, v130
	v_pk_mul_f32 v[102:103], v[102:103], v[162:163]
	v_rcp_f32_e32 v162, v130
	v_and_b32_e32 v130, 0xffff0000, v173
	v_max_f32_e32 v130, v130, v130
	v_max_f32_e32 v130, 0x1e3ce508, v130
	v_rcp_f32_e32 v163, v130
	v_lshlrev_b32_e32 v130, 16, v131
	v_and_b32_e32 v131, 0xffff0000, v131
	v_pk_mul_f32 v[130:131], v[162:163], v[130:131]
	s_nop 0
	v_pk_mul_f32 v[104:105], v[104:105], v[130:131]
	v_lshlrev_b32_e32 v130, 16, v174
	v_and_b32_e32 v131, 0xffff0000, v174
	v_max_f32_e32 v130, v130, v130
	v_max_f32_e32 v131, v131, v131
	v_max_f32_e32 v130, 0x1e3ce508, v130
	v_max_f32_e32 v131, 0x1e3ce508, v131
	v_rcp_f32_e32 v130, v130
	v_rcp_f32_e32 v131, v131
	v_lshlrev_b32_e32 v162, 16, v132
	v_and_b32_e32 v163, 0xffff0000, v132
	v_lshlrev_b32_e32 v132, 16, v133
	v_pk_mul_f32 v[130:131], v[130:131], v[162:163]
	v_and_b32_e32 v133, 0xffff0000, v133
	v_pk_mul_f32 v[98:99], v[98:99], v[130:131]
	v_lshlrev_b32_e32 v130, 16, v175
	v_and_b32_e32 v131, 0xffff0000, v175
	v_max_f32_e32 v130, v130, v130
	v_max_f32_e32 v131, v131, v131
	v_max_f32_e32 v130, 0x1e3ce508, v130
	v_max_f32_e32 v131, 0x1e3ce508, v131
	v_rcp_f32_e32 v130, v130
	v_rcp_f32_e32 v131, v131
	s_nop 0
	v_pk_mul_f32 v[130:131], v[130:131], v[132:133]
	s_nop 0
	v_pk_mul_f32 v[100:101], v[100:101], v[130:131]
	v_add_u32_e32 v130, 32, v170
	v_mad_i64_i32 v[130:131], s[26:27], v130, s82, v[134:135]
	v_lshl_add_u64 v[130:131], v[130:131], 0, s[28:29]
	v_lshl_add_u64 v[162:163], v[130:131], 0, v[136:137]
	global_load_dwordx4 v[130:133], v[162:163], off nt
	global_load_dwordx4 v[172:175], v[162:163], off offset:2048 nt
	s_waitcnt vmcnt(0)
	v_lshlrev_b32_e32 v178, 16, v130
	v_lshlrev_b32_e32 v171, 16, v172
	v_and_b32_e32 v179, 0xffff0000, v130
	v_lshlrev_b32_e32 v130, 16, v173
	v_max_f32_e32 v171, v171, v171
	v_max_f32_e32 v130, v130, v130
	v_max_f32_e32 v171, 0x1e3ce508, v171
	v_max_f32_e32 v130, 0x1e3ce508, v130
	v_rcp_f32_e32 v176, v171
	v_and_b32_e32 v171, 0xffff0000, v172
	v_rcp_f32_e32 v172, v130
	v_and_b32_e32 v130, 0xffff0000, v173
	v_max_f32_e32 v130, v130, v130
	v_max_f32_e32 v130, 0x1e3ce508, v130
	v_rcp_f32_e32 v173, v130
	v_lshlrev_b32_e32 v130, 16, v131
	v_and_b32_e32 v131, 0xffff0000, v131
	v_max_f32_e32 v171, v171, v171
	v_pk_mul_f32 v[130:131], v[172:173], v[130:131]
	v_lshlrev_b32_e32 v172, 16, v132
	v_pk_mul_f32 v[96:97], v[96:97], v[130:131]
	v_lshlrev_b32_e32 v130, 16, v174
	v_and_b32_e32 v131, 0xffff0000, v174
	v_max_f32_e32 v130, v130, v130
	v_max_f32_e32 v131, v131, v131
	v_max_f32_e32 v130, 0x1e3ce508, v130
	v_max_f32_e32 v131, 0x1e3ce508, v131
	v_rcp_f32_e32 v130, v130
	v_rcp_f32_e32 v131, v131
	v_and_b32_e32 v173, 0xffff0000, v132
	v_lshlrev_b32_e32 v132, 16, v133
	v_and_b32_e32 v133, 0xffff0000, v133
	v_pk_mul_f32 v[130:131], v[130:131], v[172:173]
	v_max_f32_e32 v171, 0x1e3ce508, v171
	v_pk_mul_f32 v[90:91], v[90:91], v[130:131]
	v_lshlrev_b32_e32 v130, 16, v175
	v_and_b32_e32 v131, 0xffff0000, v175
	v_max_f32_e32 v130, v130, v130
	v_max_f32_e32 v131, v131, v131
	v_max_f32_e32 v130, 0x1e3ce508, v130
	v_max_f32_e32 v131, 0x1e3ce508, v131
	v_rcp_f32_e32 v130, v130
	v_rcp_f32_e32 v131, v131
	v_rcp_f32_e32 v177, v171
	v_pk_mul_f32 v[130:131], v[130:131], v[132:133]
	s_nop 0
	v_pk_mul_f32 v[92:93], v[92:93], v[130:131]
	global_load_dwordx4 v[130:133], v[162:163], off offset:256 nt
	global_load_dwordx4 v[172:175], v[162:163], off offset:2304 nt
	v_pk_mul_f32 v[176:177], v[176:177], v[178:179]
	s_waitcnt vmcnt(0)
	v_lshlrev_b32_e32 v162, 16, v172
	v_and_b32_e32 v163, 0xffff0000, v172
	v_max_f32_e32 v162, v162, v162
	v_max_f32_e32 v163, v163, v163
	v_max_f32_e32 v162, 0x1e3ce508, v162
	v_max_f32_e32 v163, 0x1e3ce508, v163
	v_rcp_f32_e32 v162, v162
	v_rcp_f32_e32 v163, v163
	v_pk_mul_f32 v[94:95], v[94:95], v[176:177]
	v_lshlrev_b32_e32 v176, 16, v130
	v_and_b32_e32 v177, 0xffff0000, v130
	v_lshlrev_b32_e32 v130, 16, v173
	v_max_f32_e32 v130, v130, v130
	v_pk_mul_f32 v[162:163], v[162:163], v[176:177]
	v_max_f32_e32 v130, 0x1e3ce508, v130
	v_pk_mul_f32 v[86:87], v[86:87], v[162:163]
	v_rcp_f32_e32 v162, v130
	v_and_b32_e32 v130, 0xffff0000, v173
	v_max_f32_e32 v130, v130, v130
	v_max_f32_e32 v130, 0x1e3ce508, v130
	v_rcp_f32_e32 v163, v130
	v_lshlrev_b32_e32 v130, 16, v131
	v_and_b32_e32 v131, 0xffff0000, v131
	v_pk_mul_f32 v[130:131], v[162:163], v[130:131]
	s_nop 0
	v_pk_mul_f32 v[88:89], v[88:89], v[130:131]
	v_lshlrev_b32_e32 v130, 16, v174
	v_and_b32_e32 v131, 0xffff0000, v174
	v_max_f32_e32 v130, v130, v130
	v_max_f32_e32 v131, v131, v131
	v_max_f32_e32 v130, 0x1e3ce508, v130
	v_max_f32_e32 v131, 0x1e3ce508, v131
	v_rcp_f32_e32 v130, v130
	v_rcp_f32_e32 v131, v131
	v_lshlrev_b32_e32 v162, 16, v132
	v_and_b32_e32 v163, 0xffff0000, v132
	v_lshlrev_b32_e32 v132, 16, v133
	v_pk_mul_f32 v[130:131], v[130:131], v[162:163]
	v_and_b32_e32 v133, 0xffff0000, v133
	v_pk_mul_f32 v[82:83], v[82:83], v[130:131]
	v_lshlrev_b32_e32 v130, 16, v175
	v_and_b32_e32 v131, 0xffff0000, v175
	v_max_f32_e32 v130, v130, v130
	v_max_f32_e32 v131, v131, v131
	v_max_f32_e32 v130, 0x1e3ce508, v130
	v_max_f32_e32 v131, 0x1e3ce508, v131
	v_rcp_f32_e32 v130, v130
	v_rcp_f32_e32 v131, v131
	s_nop 0
	v_pk_mul_f32 v[130:131], v[130:131], v[132:133]
	s_nop 0
	v_pk_mul_f32 v[84:85], v[84:85], v[130:131]
	v_add_u32_e32 v130, 48, v170
	v_mad_i64_i32 v[130:131], s[26:27], v130, s82, v[134:135]
	v_lshl_add_u64 v[130:131], v[130:131], 0, s[28:29]
	v_lshl_add_u64 v[162:163], v[130:131], 0, v[136:137]
	global_load_dwordx4 v[130:133], v[162:163], off nt
	global_load_dwordx4 v[172:175], v[162:163], off offset:2048 nt
	s_waitcnt vmcnt(0)
; __device__ __forceinline__ float bflo(unsigned w) { return __uint_as_float(w << 16); }
; __device__ __forceinline__ float bfhi(unsigned w) { return __uint_as_float(w & 0xffff0000u); }
;     __device__ __forceinline__ void mid(f32x4 (&acc)[2][2][4][2], const pg8::Unit& u, int seg, int wr, int wc, int fr, int fq) const {
;     ...
;                 const bf16_t* gp = gates + (size_t)(row0 + ai * 128 + m * 16) * 3072 + seg * 1024 + col0;
; #pragma unroll
;                 for (int bj = 0; bj < 2; ++bj) {
;                     const u32x4 gw = *(const u32x4*)(gp + bj * 128), hw = *(const u32x4*)(gp + 1024 + bj * 128);
;                     f32x4 v0 = acc[ai][bj][m][0], v1 = acc[ai][bj][m][1];
;                     v0[0] *= bflo(gw.x) * __builtin_amdgcn_rcpf(fmaxf(bflo(hw.x), 1e-20f)); v0[1] *= bfhi(gw.x) * __builtin_amdgcn_rcpf(fmaxf(bfhi(hw.x), 1e-20f));
;                     v0[2] *= bflo(gw.y) * __builtin_amdgcn_rcpf(fmaxf(bflo(hw.y), 1e-20f)); v0[3] *= bfhi(gw.y) * __builtin_amdgcn_rcpf(fmaxf(bfhi(hw.y), 1e-20f));
;                     v1[0] *= bflo(gw.z) * __builtin_amdgcn_rcpf(fmaxf(bflo(hw.z), 1e-20f)); v1[1] *= bfhi(gw.z) * __builtin_amdgcn_rcpf(fmaxf(bfhi(hw.z), 1e-20f));
;                     v1[2] *= bflo(gw.w) * __builtin_amdgcn_rcpf(fmaxf(bflo(hw.w), 1e-20f)); v1[3] *= bfhi(gw.w) * __builtin_amdgcn_rcpf(fmaxf(bfhi(hw.w), 1e-20f));
;                     acc[ai][bj][m][0] = v0; acc[ai][bj][m][1] = v1;
	v_lshlrev_b32_e32 v178, 16, v130
	v_lshlrev_b32_e32 v171, 16, v172
	v_and_b32_e32 v179, 0xffff0000, v130
	v_lshlrev_b32_e32 v130, 16, v173
	v_max_f32_e32 v171, v171, v171
	v_max_f32_e32 v130, v130, v130
	v_max_f32_e32 v171, 0x1e3ce508, v171
	v_max_f32_e32 v130, 0x1e3ce508, v130
	v_rcp_f32_e32 v176, v171
	v_and_b32_e32 v171, 0xffff0000, v172
	v_rcp_f32_e32 v172, v130
	v_and_b32_e32 v130, 0xffff0000, v173
	v_max_f32_e32 v130, v130, v130
	v_max_f32_e32 v130, 0x1e3ce508, v130
	v_rcp_f32_e32 v173, v130
	v_lshlrev_b32_e32 v130, 16, v131
	v_and_b32_e32 v131, 0xffff0000, v131
	v_max_f32_e32 v171, v171, v171
	v_pk_mul_f32 v[130:131], v[172:173], v[130:131]
	v_lshlrev_b32_e32 v172, 16, v132
	v_pk_mul_f32 v[80:81], v[80:81], v[130:131]
	v_lshlrev_b32_e32 v130, 16, v174
	v_and_b32_e32 v131, 0xffff0000, v174
	v_max_f32_e32 v130, v130, v130
	v_max_f32_e32 v131, v131, v131
	v_max_f32_e32 v130, 0x1e3ce508, v130
	v_max_f32_e32 v131, 0x1e3ce508, v131
	v_rcp_f32_e32 v130, v130
	v_rcp_f32_e32 v131, v131
	v_and_b32_e32 v173, 0xffff0000, v132
	v_lshlrev_b32_e32 v132, 16, v133
	v_and_b32_e32 v133, 0xffff0000, v133
	v_pk_mul_f32 v[130:131], v[130:131], v[172:173]
	v_max_f32_e32 v171, 0x1e3ce508, v171
	v_pk_mul_f32 v[74:75], v[74:75], v[130:131]
	v_lshlrev_b32_e32 v130, 16, v175
	v_and_b32_e32 v131, 0xffff0000, v175
	v_max_f32_e32 v130, v130, v130
	v_max_f32_e32 v131, v131, v131
	v_max_f32_e32 v130, 0x1e3ce508, v130
	v_max_f32_e32 v131, 0x1e3ce508, v131
	v_rcp_f32_e32 v130, v130
	v_rcp_f32_e32 v131, v131
	v_rcp_f32_e32 v177, v171
	v_pk_mul_f32 v[130:131], v[130:131], v[132:133]
	s_nop 0
	v_pk_mul_f32 v[76:77], v[76:77], v[130:131]
	global_load_dwordx4 v[130:133], v[162:163], off offset:256 nt
	global_load_dwordx4 v[172:175], v[162:163], off offset:2304 nt
	v_pk_mul_f32 v[176:177], v[176:177], v[178:179]
	s_waitcnt vmcnt(0)
	v_lshlrev_b32_e32 v162, 16, v172
	v_and_b32_e32 v163, 0xffff0000, v172
	v_max_f32_e32 v162, v162, v162
	v_max_f32_e32 v163, v163, v163
	v_max_f32_e32 v162, 0x1e3ce508, v162
	v_max_f32_e32 v163, 0x1e3ce508, v163
	v_rcp_f32_e32 v162, v162
	v_rcp_f32_e32 v163, v163
	v_pk_mul_f32 v[78:79], v[78:79], v[176:177]
	v_lshlrev_b32_e32 v176, 16, v130
	v_and_b32_e32 v177, 0xffff0000, v130
	v_lshlrev_b32_e32 v130, 16, v173
	v_max_f32_e32 v130, v130, v130
	v_pk_mul_f32 v[162:163], v[162:163], v[176:177]
	v_max_f32_e32 v130, 0x1e3ce508, v130
	v_pk_mul_f32 v[70:71], v[70:71], v[162:163]
	v_rcp_f32_e32 v162, v130
	v_and_b32_e32 v130, 0xffff0000, v173
	v_max_f32_e32 v130, v130, v130
	v_max_f32_e32 v130, 0x1e3ce508, v130
	v_rcp_f32_e32 v163, v130
	v_lshlrev_b32_e32 v130, 16, v131
	v_and_b32_e32 v131, 0xffff0000, v131
	v_pk_mul_f32 v[130:131], v[162:163], v[130:131]
	s_nop 0
	v_pk_mul_f32 v[72:73], v[72:73], v[130:131]
	v_lshlrev_b32_e32 v130, 16, v174
	v_and_b32_e32 v131, 0xffff0000, v174
	v_max_f32_e32 v130, v130, v130
	v_max_f32_e32 v131, v131, v131
	v_max_f32_e32 v130, 0x1e3ce508, v130
	v_max_f32_e32 v131, 0x1e3ce508, v131
	v_rcp_f32_e32 v130, v130
	v_rcp_f32_e32 v131, v131
	v_lshlrev_b32_e32 v162, 16, v132
	v_and_b32_e32 v163, 0xffff0000, v132
	v_lshlrev_b32_e32 v132, 16, v133
	v_pk_mul_f32 v[130:131], v[130:131], v[162:163]
	v_and_b32_e32 v133, 0xffff0000, v133
	v_pk_mul_f32 v[66:67], v[66:67], v[130:131]
	v_lshlrev_b32_e32 v130, 16, v175
	v_and_b32_e32 v131, 0xffff0000, v175
	v_max_f32_e32 v130, v130, v130
	v_max_f32_e32 v131, v131, v131
	v_max_f32_e32 v130, 0x1e3ce508, v130
	v_max_f32_e32 v131, 0x1e3ce508, v131
	v_rcp_f32_e32 v130, v130
	v_rcp_f32_e32 v131, v131
	s_nop 0
	v_pk_mul_f32 v[130:131], v[130:131], v[132:133]
	s_nop 0
	v_pk_mul_f32 v[68:69], v[68:69], v[130:131]
	v_add_u32_e32 v130, 0x80, v170
	v_mad_i64_i32 v[130:131], s[26:27], v130, s82, v[134:135]
	v_lshl_add_u64 v[130:131], v[130:131], 0, s[28:29]
	v_lshl_add_u64 v[162:163], v[130:131], 0, v[136:137]
	global_load_dwordx4 v[130:133], v[162:163], off nt
	global_load_dwordx4 v[172:175], v[162:163], off offset:2048 nt
	s_waitcnt vmcnt(0)
	v_lshlrev_b32_e32 v178, 16, v130
	v_lshlrev_b32_e32 v171, 16, v172
	v_and_b32_e32 v179, 0xffff0000, v130
	v_lshlrev_b32_e32 v130, 16, v173
	v_max_f32_e32 v171, v171, v171
	v_max_f32_e32 v130, v130, v130
	v_max_f32_e32 v171, 0x1e3ce508, v171
	v_max_f32_e32 v130, 0x1e3ce508, v130
	v_rcp_f32_e32 v176, v171
	v_and_b32_e32 v171, 0xffff0000, v172
	v_rcp_f32_e32 v172, v130
	v_and_b32_e32 v130, 0xffff0000, v173
	v_max_f32_e32 v130, v130, v130
	v_max_f32_e32 v130, 0x1e3ce508, v130
	v_rcp_f32_e32 v173, v130
	v_lshlrev_b32_e32 v130, 16, v131
	v_and_b32_e32 v131, 0xffff0000, v131
	v_max_f32_e32 v171, v171, v171
	v_pk_mul_f32 v[130:131], v[172:173], v[130:131]
	v_lshlrev_b32_e32 v172, 16, v132
	v_pk_mul_f32 v[64:65], v[64:65], v[130:131]
	v_lshlrev_b32_e32 v130, 16, v174
	v_and_b32_e32 v131, 0xffff0000, v174
	v_max_f32_e32 v130, v130, v130
	v_max_f32_e32 v131, v131, v131
	v_max_f32_e32 v130, 0x1e3ce508, v130
	v_max_f32_e32 v131, 0x1e3ce508, v131
	v_rcp_f32_e32 v130, v130
	v_rcp_f32_e32 v131, v131
	v_and_b32_e32 v173, 0xffff0000, v132
	v_lshlrev_b32_e32 v132, 16, v133
	v_and_b32_e32 v133, 0xffff0000, v133
	v_pk_mul_f32 v[130:131], v[130:131], v[172:173]
	v_max_f32_e32 v171, 0x1e3ce508, v171
	v_pk_mul_f32 v[58:59], v[58:59], v[130:131]
	v_lshlrev_b32_e32 v130, 16, v175
	v_and_b32_e32 v131, 0xffff0000, v175
	v_max_f32_e32 v130, v130, v130
	v_max_f32_e32 v131, v131, v131
	v_max_f32_e32 v130, 0x1e3ce508, v130
	v_max_f32_e32 v131, 0x1e3ce508, v131
	v_rcp_f32_e32 v130, v130
	v_rcp_f32_e32 v131, v131
	v_rcp_f32_e32 v177, v171
	v_pk_mul_f32 v[130:131], v[130:131], v[132:133]
	s_nop 0
	v_pk_mul_f32 v[60:61], v[60:61], v[130:131]
	global_load_dwordx4 v[130:133], v[162:163], off offset:256 nt
	global_load_dwordx4 v[172:175], v[162:163], off offset:2304 nt
	v_pk_mul_f32 v[176:177], v[176:177], v[178:179]
	s_waitcnt vmcnt(0)
; __device__ __forceinline__ float bflo(unsigned w) { return __uint_as_float(w << 16); }
; __device__ __forceinline__ float bfhi(unsigned w) { return __uint_as_float(w & 0xffff0000u); }
;     __device__ __forceinline__ void mid(f32x4 (&acc)[2][2][4][2], const pg8::Unit& u, int seg, int wr, int wc, int fr, int fq) const {
;     ...
;                 const bf16_t* gp = gates + (size_t)(row0 + ai * 128 + m * 16) * 3072 + seg * 1024 + col0;
; #pragma unroll
;                 for (int bj = 0; bj < 2; ++bj) {
;                     const u32x4 gw = *(const u32x4*)(gp + bj * 128), hw = *(const u32x4*)(gp + 1024 + bj * 128);
;                     f32x4 v0 = acc[ai][bj][m][0], v1 = acc[ai][bj][m][1];
;                     v0[0] *= bflo(gw.x) * __builtin_amdgcn_rcpf(fmaxf(bflo(hw.x), 1e-20f)); v0[1] *= bfhi(gw.x) * __builtin_amdgcn_rcpf(fmaxf(bfhi(hw.x), 1e-20f));
;                     v0[2] *= bflo(gw.y) * __builtin_amdgcn_rcpf(fmaxf(bflo(hw.y), 1e-20f)); v0[3] *= bfhi(gw.y) * __builtin_amdgcn_rcpf(fmaxf(bfhi(hw.y), 1e-20f));
;                     v1[0] *= bflo(gw.z) * __builtin_amdgcn_rcpf(fmaxf(bflo(hw.z), 1e-20f)); v1[1] *= bfhi(gw.z) * __builtin_amdgcn_rcpf(fmaxf(bfhi(hw.z), 1e-20f));
;                     v1[2] *= bflo(gw.w) * __builtin_amdgcn_rcpf(fmaxf(bflo(hw.w), 1e-20f)); v1[3] *= bfhi(gw.w) * __builtin_amdgcn_rcpf(fmaxf(bfhi(hw.w), 1e-20f));
;                     acc[ai][bj][m][0] = v0; acc[ai][bj][m][1] = v1;
	v_lshlrev_b32_e32 v162, 16, v172
	v_and_b32_e32 v163, 0xffff0000, v172
	v_max_f32_e32 v162, v162, v162
	v_max_f32_e32 v163, v163, v163
	v_max_f32_e32 v162, 0x1e3ce508, v162
	v_max_f32_e32 v163, 0x1e3ce508, v163
	v_rcp_f32_e32 v162, v162
	v_rcp_f32_e32 v163, v163
	v_pk_mul_f32 v[62:63], v[62:63], v[176:177]
	v_lshlrev_b32_e32 v176, 16, v130
	v_and_b32_e32 v177, 0xffff0000, v130
	v_lshlrev_b32_e32 v130, 16, v173
	v_max_f32_e32 v130, v130, v130
	v_pk_mul_f32 v[162:163], v[162:163], v[176:177]
	v_max_f32_e32 v130, 0x1e3ce508, v130
	v_pk_mul_f32 v[54:55], v[54:55], v[162:163]
	v_rcp_f32_e32 v162, v130
	v_and_b32_e32 v130, 0xffff0000, v173
	v_max_f32_e32 v130, v130, v130
	v_max_f32_e32 v130, 0x1e3ce508, v130
	v_rcp_f32_e32 v163, v130
	v_lshlrev_b32_e32 v130, 16, v131
	v_and_b32_e32 v131, 0xffff0000, v131
	v_pk_mul_f32 v[130:131], v[162:163], v[130:131]
	s_nop 0
	v_pk_mul_f32 v[56:57], v[56:57], v[130:131]
	v_lshlrev_b32_e32 v130, 16, v174
	v_and_b32_e32 v131, 0xffff0000, v174
	v_max_f32_e32 v130, v130, v130
	v_max_f32_e32 v131, v131, v131
	v_max_f32_e32 v130, 0x1e3ce508, v130
	v_max_f32_e32 v131, 0x1e3ce508, v131
	v_rcp_f32_e32 v130, v130
	v_rcp_f32_e32 v131, v131
	v_lshlrev_b32_e32 v162, 16, v132
	v_and_b32_e32 v163, 0xffff0000, v132
	v_lshlrev_b32_e32 v132, 16, v133
	v_pk_mul_f32 v[130:131], v[130:131], v[162:163]
	v_and_b32_e32 v133, 0xffff0000, v133
	v_pk_mul_f32 v[50:51], v[50:51], v[130:131]
	v_lshlrev_b32_e32 v130, 16, v175
	v_and_b32_e32 v131, 0xffff0000, v175
	v_max_f32_e32 v130, v130, v130
	v_max_f32_e32 v131, v131, v131
	v_max_f32_e32 v130, 0x1e3ce508, v130
	v_max_f32_e32 v131, 0x1e3ce508, v131
	v_rcp_f32_e32 v130, v130
	v_rcp_f32_e32 v131, v131
	s_nop 0
	v_pk_mul_f32 v[130:131], v[130:131], v[132:133]
	s_nop 0
	v_pk_mul_f32 v[52:53], v[52:53], v[130:131]
	v_add_u32_e32 v130, 0x90, v170
	v_mad_i64_i32 v[130:131], s[26:27], v130, s82, v[134:135]
	v_lshl_add_u64 v[130:131], v[130:131], 0, s[28:29]
	v_lshl_add_u64 v[162:163], v[130:131], 0, v[136:137]
	global_load_dwordx4 v[130:133], v[162:163], off nt
	global_load_dwordx4 v[172:175], v[162:163], off offset:2048 nt
	s_waitcnt vmcnt(0)
	v_lshlrev_b32_e32 v178, 16, v130
	v_lshlrev_b32_e32 v171, 16, v172
	v_and_b32_e32 v179, 0xffff0000, v130
	v_lshlrev_b32_e32 v130, 16, v173
	v_max_f32_e32 v171, v171, v171
	v_max_f32_e32 v130, v130, v130
	v_max_f32_e32 v171, 0x1e3ce508, v171
	v_max_f32_e32 v130, 0x1e3ce508, v130
	v_rcp_f32_e32 v176, v171
	v_and_b32_e32 v171, 0xffff0000, v172
	v_rcp_f32_e32 v172, v130
	v_and_b32_e32 v130, 0xffff0000, v173
	v_max_f32_e32 v130, v130, v130
	v_max_f32_e32 v130, 0x1e3ce508, v130
	v_rcp_f32_e32 v173, v130
	v_lshlrev_b32_e32 v130, 16, v131
	v_and_b32_e32 v131, 0xffff0000, v131
	v_max_f32_e32 v171, v171, v171
	v_pk_mul_f32 v[130:131], v[172:173], v[130:131]
	v_lshlrev_b32_e32 v172, 16, v132
	v_pk_mul_f32 v[48:49], v[48:49], v[130:131]
	v_lshlrev_b32_e32 v130, 16, v174
	v_and_b32_e32 v131, 0xffff0000, v174
	v_max_f32_e32 v130, v130, v130
	v_max_f32_e32 v131, v131, v131
	v_max_f32_e32 v130, 0x1e3ce508, v130
	v_max_f32_e32 v131, 0x1e3ce508, v131
	v_rcp_f32_e32 v130, v130
	v_rcp_f32_e32 v131, v131
	v_and_b32_e32 v173, 0xffff0000, v132
	v_lshlrev_b32_e32 v132, 16, v133
	v_and_b32_e32 v133, 0xffff0000, v133
	v_pk_mul_f32 v[130:131], v[130:131], v[172:173]
	v_max_f32_e32 v171, 0x1e3ce508, v171
	v_pk_mul_f32 v[42:43], v[42:43], v[130:131]
	v_lshlrev_b32_e32 v130, 16, v175
	v_and_b32_e32 v131, 0xffff0000, v175
	v_max_f32_e32 v130, v130, v130
	v_max_f32_e32 v131, v131, v131
	v_max_f32_e32 v130, 0x1e3ce508, v130
	v_max_f32_e32 v131, 0x1e3ce508, v131
	v_rcp_f32_e32 v130, v130
	v_rcp_f32_e32 v131, v131
	v_rcp_f32_e32 v177, v171
	v_pk_mul_f32 v[130:131], v[130:131], v[132:133]
	s_nop 0
	v_pk_mul_f32 v[44:45], v[44:45], v[130:131]
	global_load_dwordx4 v[130:133], v[162:163], off offset:256 nt
	global_load_dwordx4 v[172:175], v[162:163], off offset:2304 nt
	v_pk_mul_f32 v[176:177], v[176:177], v[178:179]
	s_waitcnt vmcnt(0)
	v_lshlrev_b32_e32 v162, 16, v172
	v_and_b32_e32 v163, 0xffff0000, v172
	v_max_f32_e32 v162, v162, v162
	v_max_f32_e32 v163, v163, v163
	v_max_f32_e32 v162, 0x1e3ce508, v162
	v_max_f32_e32 v163, 0x1e3ce508, v163
	v_rcp_f32_e32 v162, v162
	v_rcp_f32_e32 v163, v163
	v_pk_mul_f32 v[46:47], v[46:47], v[176:177]
	v_lshlrev_b32_e32 v176, 16, v130
	v_and_b32_e32 v177, 0xffff0000, v130
	v_lshlrev_b32_e32 v130, 16, v173
	v_max_f32_e32 v130, v130, v130
	v_pk_mul_f32 v[162:163], v[162:163], v[176:177]
	v_max_f32_e32 v130, 0x1e3ce508, v130
	v_pk_mul_f32 v[38:39], v[38:39], v[162:163]
	v_rcp_f32_e32 v162, v130
	v_and_b32_e32 v130, 0xffff0000, v173
	v_max_f32_e32 v130, v130, v130
	v_max_f32_e32 v130, 0x1e3ce508, v130
	v_rcp_f32_e32 v163, v130
	v_lshlrev_b32_e32 v130, 16, v131
	v_and_b32_e32 v131, 0xffff0000, v131
	v_pk_mul_f32 v[130:131], v[162:163], v[130:131]
	s_nop 0
	v_pk_mul_f32 v[40:41], v[40:41], v[130:131]
	v_lshlrev_b32_e32 v130, 16, v174
	v_and_b32_e32 v131, 0xffff0000, v174
	v_max_f32_e32 v130, v130, v130
	v_max_f32_e32 v131, v131, v131
	v_max_f32_e32 v130, 0x1e3ce508, v130
	v_max_f32_e32 v131, 0x1e3ce508, v131
	v_rcp_f32_e32 v130, v130
	v_rcp_f32_e32 v131, v131
	v_lshlrev_b32_e32 v162, 16, v132
	v_and_b32_e32 v163, 0xffff0000, v132
	v_lshlrev_b32_e32 v132, 16, v133
	v_pk_mul_f32 v[130:131], v[130:131], v[162:163]
	v_and_b32_e32 v133, 0xffff0000, v133
	v_pk_mul_f32 v[34:35], v[34:35], v[130:131]
	v_lshlrev_b32_e32 v130, 16, v175
	v_and_b32_e32 v131, 0xffff0000, v175
	v_max_f32_e32 v130, v130, v130
	v_max_f32_e32 v131, v131, v131
	v_max_f32_e32 v130, 0x1e3ce508, v130
	v_max_f32_e32 v131, 0x1e3ce508, v131
	v_rcp_f32_e32 v130, v130
	v_rcp_f32_e32 v131, v131
	s_nop 0
	v_pk_mul_f32 v[130:131], v[130:131], v[132:133]
	s_nop 0
	v_pk_mul_f32 v[36:37], v[36:37], v[130:131]
	v_add_u32_e32 v130, 0xa0, v170
	v_mad_i64_i32 v[130:131], s[26:27], v130, s82, v[134:135]
	v_lshl_add_u64 v[130:131], v[130:131], 0, s[28:29]
	v_lshl_add_u64 v[162:163], v[130:131], 0, v[136:137]
	global_load_dwordx4 v[130:133], v[162:163], off nt
	global_load_dwordx4 v[172:175], v[162:163], off offset:2048 nt
	s_waitcnt vmcnt(0)
; __device__ __forceinline__ float bflo(unsigned w) { return __uint_as_float(w << 16); }
; __device__ __forceinline__ float bfhi(unsigned w) { return __uint_as_float(w & 0xffff0000u); }
;     __device__ __forceinline__ void mid(f32x4 (&acc)[2][2][4][2], const pg8::Unit& u, int seg, int wr, int wc, int fr, int fq) const {
;     ...
;                 const bf16_t* gp = gates + (size_t)(row0 + ai * 128 + m * 16) * 3072 + seg * 1024 + col0;
; #pragma unroll
;                 for (int bj = 0; bj < 2; ++bj) {
;                     const u32x4 gw = *(const u32x4*)(gp + bj * 128), hw = *(const u32x4*)(gp + 1024 + bj * 128);
;                     f32x4 v0 = acc[ai][bj][m][0], v1 = acc[ai][bj][m][1];
;                     v0[0] *= bflo(gw.x) * __builtin_amdgcn_rcpf(fmaxf(bflo(hw.x), 1e-20f)); v0[1] *= bfhi(gw.x) * __builtin_amdgcn_rcpf(fmaxf(bfhi(hw.x), 1e-20f));
;                     v0[2] *= bflo(gw.y) * __builtin_amdgcn_rcpf(fmaxf(bflo(hw.y), 1e-20f)); v0[3] *= bfhi(gw.y) * __builtin_amdgcn_rcpf(fmaxf(bfhi(hw.y), 1e-20f));
;                     v1[0] *= bflo(gw.z) * __builtin_amdgcn_rcpf(fmaxf(bflo(hw.z), 1e-20f)); v1[1] *= bfhi(gw.z) * __builtin_amdgcn_rcpf(fmaxf(bfhi(hw.z), 1e-20f));
;                     v1[2] *= bflo(gw.w) * __builtin_amdgcn_rcpf(fmaxf(bflo(hw.w), 1e-20f)); v1[3] *= bfhi(gw.w) * __builtin_amdgcn_rcpf(fmaxf(bfhi(hw.w), 1e-20f));
;                     acc[ai][bj][m][0] = v0; acc[ai][bj][m][1] = v1;
	v_lshlrev_b32_e32 v178, 16, v130
	v_lshlrev_b32_e32 v171, 16, v172
	v_and_b32_e32 v179, 0xffff0000, v130
	v_lshlrev_b32_e32 v130, 16, v173
	v_max_f32_e32 v171, v171, v171
	v_max_f32_e32 v130, v130, v130
	v_max_f32_e32 v171, 0x1e3ce508, v171
	v_max_f32_e32 v130, 0x1e3ce508, v130
	v_rcp_f32_e32 v176, v171
	v_and_b32_e32 v171, 0xffff0000, v172
	v_rcp_f32_e32 v172, v130
	v_and_b32_e32 v130, 0xffff0000, v173
	v_max_f32_e32 v130, v130, v130
	v_max_f32_e32 v130, 0x1e3ce508, v130
	v_rcp_f32_e32 v173, v130
	v_lshlrev_b32_e32 v130, 16, v131
	v_and_b32_e32 v131, 0xffff0000, v131
	v_max_f32_e32 v171, v171, v171
	v_pk_mul_f32 v[130:131], v[172:173], v[130:131]
	v_lshlrev_b32_e32 v172, 16, v132
	v_pk_mul_f32 v[32:33], v[32:33], v[130:131]
	v_lshlrev_b32_e32 v130, 16, v174
	v_and_b32_e32 v131, 0xffff0000, v174
	v_max_f32_e32 v130, v130, v130
	v_max_f32_e32 v131, v131, v131
	v_max_f32_e32 v130, 0x1e3ce508, v130
	v_max_f32_e32 v131, 0x1e3ce508, v131
	v_rcp_f32_e32 v130, v130
	v_rcp_f32_e32 v131, v131
	v_and_b32_e32 v173, 0xffff0000, v132
	v_lshlrev_b32_e32 v132, 16, v133
	v_and_b32_e32 v133, 0xffff0000, v133
	v_pk_mul_f32 v[130:131], v[130:131], v[172:173]
	v_max_f32_e32 v171, 0x1e3ce508, v171
	v_pk_mul_f32 v[26:27], v[26:27], v[130:131]
	v_lshlrev_b32_e32 v130, 16, v175
	v_and_b32_e32 v131, 0xffff0000, v175
	v_max_f32_e32 v130, v130, v130
	v_max_f32_e32 v131, v131, v131
	v_max_f32_e32 v130, 0x1e3ce508, v130
	v_max_f32_e32 v131, 0x1e3ce508, v131
	v_rcp_f32_e32 v130, v130
	v_rcp_f32_e32 v131, v131
	v_rcp_f32_e32 v177, v171
	v_pk_mul_f32 v[130:131], v[130:131], v[132:133]
	s_nop 0
	v_pk_mul_f32 v[28:29], v[28:29], v[130:131]
	global_load_dwordx4 v[130:133], v[162:163], off offset:256 nt
	global_load_dwordx4 v[172:175], v[162:163], off offset:2304 nt
	v_pk_mul_f32 v[176:177], v[176:177], v[178:179]
	s_waitcnt vmcnt(0)
	v_lshlrev_b32_e32 v162, 16, v172
	v_and_b32_e32 v163, 0xffff0000, v172
	v_max_f32_e32 v162, v162, v162
	v_max_f32_e32 v163, v163, v163
	v_max_f32_e32 v162, 0x1e3ce508, v162
	v_max_f32_e32 v163, 0x1e3ce508, v163
	v_rcp_f32_e32 v162, v162
	v_rcp_f32_e32 v163, v163
	v_pk_mul_f32 v[30:31], v[30:31], v[176:177]
	v_lshlrev_b32_e32 v176, 16, v130
	v_and_b32_e32 v177, 0xffff0000, v130
	v_lshlrev_b32_e32 v130, 16, v173
	v_max_f32_e32 v130, v130, v130
	v_pk_mul_f32 v[162:163], v[162:163], v[176:177]
	v_max_f32_e32 v130, 0x1e3ce508, v130
	v_pk_mul_f32 v[22:23], v[22:23], v[162:163]
	v_rcp_f32_e32 v162, v130
	v_and_b32_e32 v130, 0xffff0000, v173
	v_max_f32_e32 v130, v130, v130
	v_max_f32_e32 v130, 0x1e3ce508, v130
	v_rcp_f32_e32 v163, v130
	v_lshlrev_b32_e32 v130, 16, v131
	v_and_b32_e32 v131, 0xffff0000, v131
	v_pk_mul_f32 v[130:131], v[162:163], v[130:131]
	s_nop 0
	v_pk_mul_f32 v[24:25], v[24:25], v[130:131]
	v_lshlrev_b32_e32 v130, 16, v174
	v_and_b32_e32 v131, 0xffff0000, v174
	v_max_f32_e32 v130, v130, v130
	v_max_f32_e32 v131, v131, v131
	v_max_f32_e32 v130, 0x1e3ce508, v130
	v_max_f32_e32 v131, 0x1e3ce508, v131
	v_rcp_f32_e32 v130, v130
	v_rcp_f32_e32 v131, v131
	v_lshlrev_b32_e32 v162, 16, v132
	v_and_b32_e32 v163, 0xffff0000, v132
	v_lshlrev_b32_e32 v132, 16, v133
	v_pk_mul_f32 v[130:131], v[130:131], v[162:163]
	v_and_b32_e32 v133, 0xffff0000, v133
	v_pk_mul_f32 v[18:19], v[18:19], v[130:131]
	v_lshlrev_b32_e32 v130, 16, v175
	v_and_b32_e32 v131, 0xffff0000, v175
	v_max_f32_e32 v130, v130, v130
	v_max_f32_e32 v131, v131, v131
	v_max_f32_e32 v130, 0x1e3ce508, v130
	v_max_f32_e32 v131, 0x1e3ce508, v131
	v_rcp_f32_e32 v130, v130
	v_rcp_f32_e32 v131, v131
	s_nop 0
	v_pk_mul_f32 v[130:131], v[130:131], v[132:133]
	s_nop 0
	v_pk_mul_f32 v[20:21], v[20:21], v[130:131]
	v_add_u32_e32 v130, 0xb0, v170
	v_mad_i64_i32 v[130:131], s[26:27], v130, s82, v[134:135]
	v_lshl_add_u64 v[130:131], v[130:131], 0, s[28:29]
	v_lshl_add_u64 v[134:135], v[130:131], 0, v[136:137]
	global_load_dwordx4 v[130:133], v[134:135], off nt
	global_load_dwordx4 v[170:173], v[134:135], off offset:2048 nt
	s_waitcnt vmcnt(0)
; __device__ __forceinline__ float bflo(unsigned w) { return __uint_as_float(w << 16); }
; __device__ __forceinline__ float bfhi(unsigned w) { return __uint_as_float(w & 0xffff0000u); }
;     __device__ __forceinline__ void mid(f32x4 (&acc)[2][2][4][2], const pg8::Unit& u, int seg, int wr, int wc, int fr, int fq) const {
;     ...
;                 const bf16_t* gp = gates + (size_t)(row0 + ai * 128 + m * 16) * 3072 + seg * 1024 + col0;
; #pragma unroll
;                 for (int bj = 0; bj < 2; ++bj) {
;                     const u32x4 gw = *(const u32x4*)(gp + bj * 128), hw = *(const u32x4*)(gp + 1024 + bj * 128);
;                     f32x4 v0 = acc[ai][bj][m][0], v1 = acc[ai][bj][m][1];
;                     v0[0] *= bflo(gw.x) * __builtin_amdgcn_rcpf(fmaxf(bflo(hw.x), 1e-20f)); v0[1] *= bfhi(gw.x) * __builtin_amdgcn_rcpf(fmaxf(bfhi(hw.x), 1e-20f));
;                     v0[2] *= bflo(gw.y) * __builtin_amdgcn_rcpf(fmaxf(bflo(hw.y), 1e-20f)); v0[3] *= bfhi(gw.y) * __builtin_amdgcn_rcpf(fmaxf(bfhi(hw.y), 1e-20f));
;                     v1[0] *= bflo(gw.z) * __builtin_amdgcn_rcpf(fmaxf(bflo(hw.z), 1e-20f)); v1[1] *= bfhi(gw.z) * __builtin_amdgcn_rcpf(fmaxf(bfhi(hw.z), 1e-20f));
;                     v1[2] *= bflo(gw.w) * __builtin_amdgcn_rcpf(fmaxf(bflo(hw.w), 1e-20f)); v1[3] *= bfhi(gw.w) * __builtin_amdgcn_rcpf(fmaxf(bfhi(hw.w), 1e-20f));
;                     acc[ai][bj][m][0] = v0; acc[ai][bj][m][1] = v1;
	v_lshlrev_b32_e32 v162, 16, v130
	v_lshlrev_b32_e32 v136, 16, v170
	v_and_b32_e32 v137, 0xffff0000, v170
	v_max_f32_e32 v136, v136, v136
	v_max_f32_e32 v137, v137, v137
	v_max_f32_e32 v136, 0x1e3ce508, v136
	v_max_f32_e32 v137, 0x1e3ce508, v137
	v_rcp_f32_e32 v136, v136
	v_rcp_f32_e32 v137, v137
	v_and_b32_e32 v163, 0xffff0000, v130
	v_lshlrev_b32_e32 v130, 16, v171
	v_max_f32_e32 v130, v130, v130
	v_pk_mul_f32 v[136:137], v[136:137], v[162:163]
	v_max_f32_e32 v130, 0x1e3ce508, v130
	v_pk_mul_f32 v[14:15], v[14:15], v[136:137]
	v_rcp_f32_e32 v136, v130
	v_and_b32_e32 v130, 0xffff0000, v171
	v_max_f32_e32 v130, v130, v130
	v_max_f32_e32 v130, 0x1e3ce508, v130
	v_rcp_f32_e32 v137, v130
	v_lshlrev_b32_e32 v130, 16, v131
	v_and_b32_e32 v131, 0xffff0000, v131
	v_pk_mul_f32 v[130:131], v[136:137], v[130:131]
	s_nop 0
	v_pk_mul_f32 v[16:17], v[16:17], v[130:131]
	v_lshlrev_b32_e32 v130, 16, v172
	v_and_b32_e32 v131, 0xffff0000, v172
	v_max_f32_e32 v130, v130, v130
	v_max_f32_e32 v131, v131, v131
	v_max_f32_e32 v130, 0x1e3ce508, v130
	v_max_f32_e32 v131, 0x1e3ce508, v131
	v_rcp_f32_e32 v130, v130
	v_rcp_f32_e32 v131, v131
	v_lshlrev_b32_e32 v136, 16, v132
	v_and_b32_e32 v137, 0xffff0000, v132
	v_lshlrev_b32_e32 v132, 16, v133
	v_pk_mul_f32 v[130:131], v[130:131], v[136:137]
	v_and_b32_e32 v133, 0xffff0000, v133
	v_pk_mul_f32 v[10:11], v[10:11], v[130:131]
	v_lshlrev_b32_e32 v130, 16, v173
	v_and_b32_e32 v131, 0xffff0000, v173
	v_max_f32_e32 v130, v130, v130
	v_max_f32_e32 v131, v131, v131
	v_max_f32_e32 v130, 0x1e3ce508, v130
	v_max_f32_e32 v131, 0x1e3ce508, v131
	v_rcp_f32_e32 v130, v130
	v_rcp_f32_e32 v131, v131
	s_nop 0
	v_pk_mul_f32 v[130:131], v[130:131], v[132:133]
	s_nop 0
	v_pk_mul_f32 v[12:13], v[12:13], v[130:131]
	global_load_dwordx4 v[130:133], v[134:135], off offset:256 nt
	s_nop 0
	global_load_dwordx4 v[134:137], v[134:135], off offset:2304 nt
	s_waitcnt vmcnt(0)
	v_lshlrev_b32_e32 v170, 16, v130
	v_lshlrev_b32_e32 v162, 16, v134
	v_and_b32_e32 v134, 0xffff0000, v134
	v_and_b32_e32 v171, 0xffff0000, v130
	v_lshlrev_b32_e32 v130, 16, v135
	v_max_f32_e32 v134, v134, v134
	v_max_f32_e32 v130, v130, v130
	v_max_f32_e32 v134, 0x1e3ce508, v134
	v_max_f32_e32 v130, 0x1e3ce508, v130
	v_rcp_f32_e32 v163, v134
	v_rcp_f32_e32 v134, v130
	v_and_b32_e32 v130, 0xffff0000, v135
	v_max_f32_e32 v130, v130, v130
	v_max_f32_e32 v130, 0x1e3ce508, v130
	v_rcp_f32_e32 v135, v130
	v_lshlrev_b32_e32 v130, 16, v131
	v_and_b32_e32 v131, 0xffff0000, v131
	v_max_f32_e32 v162, v162, v162
	v_pk_mul_f32 v[130:131], v[134:135], v[130:131]
	v_lshlrev_b32_e32 v134, 16, v132
	v_pk_mul_f32 v[8:9], v[8:9], v[130:131]
	v_lshlrev_b32_e32 v130, 16, v136
	v_and_b32_e32 v131, 0xffff0000, v136
	v_max_f32_e32 v130, v130, v130
	v_max_f32_e32 v131, v131, v131
	v_max_f32_e32 v130, 0x1e3ce508, v130
	v_max_f32_e32 v131, 0x1e3ce508, v131
	v_rcp_f32_e32 v130, v130
	v_rcp_f32_e32 v131, v131
	v_and_b32_e32 v135, 0xffff0000, v132
	v_max_f32_e32 v162, 0x1e3ce508, v162
	v_rcp_f32_e32 v162, v162
	v_pk_mul_f32 v[130:131], v[130:131], v[134:135]
	v_lshlrev_b32_e32 v132, 16, v133
	v_pk_mul_f32 v[2:3], v[2:3], v[130:131]
	v_lshlrev_b32_e32 v130, 16, v137
	v_and_b32_e32 v131, 0xffff0000, v137
	v_max_f32_e32 v130, v130, v130
	v_max_f32_e32 v131, v131, v131
	v_max_f32_e32 v130, 0x1e3ce508, v130
	v_max_f32_e32 v131, 0x1e3ce508, v131
	v_rcp_f32_e32 v130, v130
	v_rcp_f32_e32 v131, v131
	v_and_b32_e32 v133, 0xffff0000, v133
	v_pk_mul_f32 v[162:163], v[162:163], v[170:171]
	v_pk_mul_f32 v[130:131], v[130:131], v[132:133]
	v_pk_mul_f32 v[6:7], v[6:7], v[162:163]
	v_pk_mul_f32 v[4:5], v[4:5], v[130:131]
	s_branch .LBB0_103

; __device__ __forceinline__ unsigned cvt_pk_bf16(float lo, float hi) { unsigned r; asm volatile("v_cvt_pk_bf16_f32 %0, %1, %2" : "=v"(r) : "v"(lo), "v"(hi)); return r; }
; __device__ __forceinline__ float bflo(unsigned w) { return __uint_as_float(w << 16); }
; __device__ __forceinline__ float bfhi(unsigned w) { return __uint_as_float(w & 0xffff0000u); }
;     __device__ __forceinline__ void operator()(f32x4 (&acc)[2][2][4][2], const pg8::Unit& u, int wr, int wc, int fr, int fq, LAS unsigned char*) const {
;     ...
;                 const int row = row0 + ai * 128 + m * 16;
; #pragma unroll
;                 for (int bj = 0; bj < 2; ++bj) {
;                     const int col = col0 + bj * 128;
;                     const u32x4 gw = *(const u32x4*)(gates + (size_t)row * 3072 + 2048 + col);
;                     const f32x4 v0 = acc[ai][bj][m][0], v1 = acc[ai][bj][m][1];
;                     u32x4 w; w.x = cvt_pk_bf16(v0[0] * bflo(gw.x), v0[1] * bfhi(gw.x)); w.y = cvt_pk_bf16(v0[2] * bflo(gw.y), v0[3] * bfhi(gw.y));
;                     w.z = cvt_pk_bf16(v1[0] * bflo(gw.z), v1[1] * bfhi(gw.z)); w.w = cvt_pk_bf16(v1[2] * bflo(gw.w), v1[3] * bfhi(gw.w));
;                     *(u32x4*)(Y + (size_t)row * DM + col) = w;
.LBB0_114:
	v_add_u32_e32 v134, s23, v166
	v_or_b32_e32 v132, s84, v168
	v_mov_b64_e32 v[136:137], s[12:13]
	v_mad_i64_i32 v[130:131], s[26:27], v134, s82, v[136:137]
	v_ashrrev_i32_e32 v133, 31, v132
	v_lshl_add_u64 v[162:163], v[130:131], 0, s[38:39]
	v_lshlrev_b64 v[130:131], 1, v[132:133]
	v_lshl_add_u64 v[158:159], v[162:163], 0, v[130:131]
	global_load_dwordx4 v[158:161], v[158:159], off nt
	v_or_b32_e32 v132, 0x80, v132
	v_ashrrev_i32_e32 v133, 31, v132
	v_lshlrev_b64 v[132:133], 1, v[132:133]
	v_lshl_add_u64 v[162:163], v[162:163], 0, v[132:133]
	s_andn2_b64 vcc, exec, s[4:5]
	s_mov_b64 s[4:5], -1
	s_waitcnt vmcnt(0)
	v_lshlrev_b32_e32 v135, 16, v158
	v_and_b32_e32 v158, 0xffff0000, v158
	v_lshlrev_b32_e32 v170, 16, v159
	v_and_b32_e32 v159, 0xffff0000, v159
	v_lshlrev_b32_e32 v172, 16, v161
	v_and_b32_e32 v161, 0xffff0000, v161
	v_lshlrev_b32_e32 v171, 16, v160
	v_and_b32_e32 v160, 0xffff0000, v160
	v_mul_f32_e32 v126, v126, v135
	v_mul_f32_e32 v127, v127, v158
	v_mul_f32_e32 v128, v128, v170
	v_mul_f32_e32 v129, v129, v159
	v_mul_f32_e32 v125, v125, v161
	v_mul_f32_e32 v135, v122, v171
	v_mul_f32_e32 v158, v123, v160
	v_mul_f32_e32 v159, v124, v172
	v_cvt_pk_bf16_f32 v122, v126, v127
	v_cvt_pk_bf16_f32 v123, v128, v129
	v_cvt_pk_bf16_f32 v124, v135, v158
	v_cvt_pk_bf16_f32 v125, v159, v125
	global_load_dwordx4 v[126:129], v[162:163], off nt
	v_ashrrev_i32_e32 v135, 31, v134
	v_lshlrev_b64 v[160:161], 11, v[134:135]
	v_or_b32_e32 v158, 16, v134
	v_lshl_add_u64 v[160:161], s[14:15], 0, v[160:161]
	v_mad_i64_i32 v[162:163], s[26:27], v158, s82, v[136:137]
	v_lshl_add_u64 v[160:161], v[160:161], 0, v[130:131]
	v_lshl_add_u64 v[162:163], v[162:163], 0, s[38:39]
	global_store_dwordx4 v[160:161], v[122:125], off
	v_lshl_add_u64 v[170:171], v[162:163], 0, v[130:131]
	v_ashrrev_i32_e32 v159, 31, v158
	s_waitcnt vmcnt(1)
	v_lshlrev_b32_e32 v122, 16, v126
	v_and_b32_e32 v123, 0xffff0000, v126
	v_lshlrev_b32_e32 v124, 16, v127
	v_and_b32_e32 v125, 0xffff0000, v127
	v_lshlrev_b32_e32 v126, 16, v128
	v_and_b32_e32 v127, 0xffff0000, v128
	v_lshlrev_b32_e32 v128, 16, v129
	v_and_b32_e32 v129, 0xffff0000, v129
	v_mul_f32_e32 v118, v118, v122
	v_mul_f32_e32 v119, v119, v123
	v_mul_f32_e32 v120, v120, v124
	v_mul_f32_e32 v121, v121, v125
	v_mul_f32_e32 v117, v117, v129
	v_mul_f32_e32 v122, v114, v126
	v_mul_f32_e32 v123, v115, v127
	v_mul_f32_e32 v124, v116, v128
	v_cvt_pk_bf16_f32 v114, v118, v119
	v_cvt_pk_bf16_f32 v115, v120, v121
	v_cvt_pk_bf16_f32 v116, v122, v123
	v_cvt_pk_bf16_f32 v117, v124, v117
	global_load_dwordx4 v[118:121], v[170:171], off nt
	v_lshl_add_u64 v[122:123], v[162:163], 0, v[132:133]
	global_store_dwordx4 v[160:161], v[114:117], off offset:256
	s_waitcnt vmcnt(1)
	s_nop 0
	v_lshlrev_b32_e32 v114, 16, v118
	v_and_b32_e32 v115, 0xffff0000, v118
	v_lshlrev_b32_e32 v116, 16, v119
	v_and_b32_e32 v117, 0xffff0000, v119
	v_lshlrev_b32_e32 v118, 16, v120
	v_and_b32_e32 v119, 0xffff0000, v120
	v_lshlrev_b32_e32 v120, 16, v121
	v_and_b32_e32 v121, 0xffff0000, v121
	v_mul_f32_e32 v110, v110, v114
	v_mul_f32_e32 v111, v111, v115
	v_mul_f32_e32 v112, v112, v116
	v_mul_f32_e32 v113, v113, v117
	v_mul_f32_e32 v109, v109, v121
	v_mul_f32_e32 v114, v106, v118
	v_mul_f32_e32 v115, v107, v119
	v_mul_f32_e32 v116, v108, v120
	v_cvt_pk_bf16_f32 v106, v110, v111
	v_cvt_pk_bf16_f32 v107, v112, v113
	v_cvt_pk_bf16_f32 v108, v114, v115
	v_cvt_pk_bf16_f32 v109, v116, v109
	global_load_dwordx4 v[110:113], v[122:123], off nt
	v_lshlrev_b64 v[118:119], 11, v[158:159]
	v_or_b32_e32 v114, 32, v134
	v_lshl_add_u64 v[118:119], s[14:15], 0, v[118:119]
	v_mad_i64_i32 v[116:117], s[26:27], v114, s82, v[136:137]
	v_lshl_add_u64 v[118:119], v[118:119], 0, v[130:131]
	v_lshl_add_u64 v[116:117], v[116:117], 0, s[38:39]
	global_store_dwordx4 v[118:119], v[106:109], off
	v_lshl_add_u64 v[120:121], v[116:117], 0, v[130:131]
	v_ashrrev_i32_e32 v115, 31, v114
	s_waitcnt vmcnt(1)
	v_lshlrev_b32_e32 v106, 16, v110
	v_and_b32_e32 v107, 0xffff0000, v110
	v_lshlrev_b32_e32 v108, 16, v111
	v_and_b32_e32 v109, 0xffff0000, v111
	v_lshlrev_b32_e32 v110, 16, v112
	v_and_b32_e32 v111, 0xffff0000, v112
	v_lshlrev_b32_e32 v112, 16, v113
	v_and_b32_e32 v113, 0xffff0000, v113
	v_mul_f32_e32 v102, v102, v106
	v_mul_f32_e32 v103, v103, v107
	v_mul_f32_e32 v104, v104, v108
	v_mul_f32_e32 v105, v105, v109
	v_mul_f32_e32 v101, v101, v113
	v_mul_f32_e32 v106, v98, v110
	v_mul_f32_e32 v107, v99, v111
	v_mul_f32_e32 v108, v100, v112
	v_cvt_pk_bf16_f32 v98, v102, v103
	v_cvt_pk_bf16_f32 v99, v104, v105
	v_cvt_pk_bf16_f32 v100, v106, v107
	v_cvt_pk_bf16_f32 v101, v108, v101
	global_load_dwordx4 v[102:105], v[120:121], off nt
	v_lshl_add_u64 v[106:107], v[116:117], 0, v[132:133]
	global_store_dwordx4 v[118:119], v[98:101], off offset:256
	s_waitcnt vmcnt(1)
	s_nop 0
	v_lshlrev_b32_e32 v98, 16, v102
	v_and_b32_e32 v99, 0xffff0000, v102
	v_lshlrev_b32_e32 v100, 16, v103
	v_and_b32_e32 v101, 0xffff0000, v103
	v_lshlrev_b32_e32 v102, 16, v104
	v_and_b32_e32 v103, 0xffff0000, v104
	v_lshlrev_b32_e32 v104, 16, v105
	v_and_b32_e32 v105, 0xffff0000, v105
	v_mul_f32_e32 v94, v94, v98
	v_mul_f32_e32 v95, v95, v99
	v_mul_f32_e32 v96, v96, v100
	v_mul_f32_e32 v97, v97, v101
	v_mul_f32_e32 v93, v93, v105
	v_mul_f32_e32 v98, v90, v102
	v_mul_f32_e32 v99, v91, v103
	v_mul_f32_e32 v100, v92, v104
	v_cvt_pk_bf16_f32 v90, v94, v95
	v_cvt_pk_bf16_f32 v91, v96, v97
	v_cvt_pk_bf16_f32 v92, v98, v99
	v_cvt_pk_bf16_f32 v93, v100, v93
	global_load_dwordx4 v[94:97], v[106:107], off nt
	v_lshlrev_b64 v[102:103], 11, v[114:115]
	v_or_b32_e32 v98, 48, v134
	v_lshl_add_u64 v[102:103], s[14:15], 0, v[102:103]
	v_mad_i64_i32 v[100:101], s[26:27], v98, s82, v[136:137]
	v_lshl_add_u64 v[102:103], v[102:103], 0, v[130:131]
	v_lshl_add_u64 v[100:101], v[100:101], 0, s[38:39]
	global_store_dwordx4 v[102:103], v[90:93], off
	v_lshl_add_u64 v[104:105], v[100:101], 0, v[130:131]
	v_ashrrev_i32_e32 v99, 31, v98
	s_waitcnt vmcnt(1)
; __device__ __forceinline__ unsigned cvt_pk_bf16(float lo, float hi) { unsigned r; asm volatile("v_cvt_pk_bf16_f32 %0, %1, %2" : "=v"(r) : "v"(lo), "v"(hi)); return r; }
; __device__ __forceinline__ float bflo(unsigned w) { return __uint_as_float(w << 16); }
; __device__ __forceinline__ float bfhi(unsigned w) { return __uint_as_float(w & 0xffff0000u); }
;     __device__ __forceinline__ void operator()(f32x4 (&acc)[2][2][4][2], const pg8::Unit& u, int wr, int wc, int fr, int fq, LAS unsigned char*) const {
;     ...
;                 const int row = row0 + ai * 128 + m * 16;
; #pragma unroll
;                 for (int bj = 0; bj < 2; ++bj) {
;                     const int col = col0 + bj * 128;
;                     const u32x4 gw = *(const u32x4*)(gates + (size_t)row * 3072 + 2048 + col);
;                     const f32x4 v0 = acc[ai][bj][m][0], v1 = acc[ai][bj][m][1];
;                     u32x4 w; w.x = cvt_pk_bf16(v0[0] * bflo(gw.x), v0[1] * bfhi(gw.x)); w.y = cvt_pk_bf16(v0[2] * bflo(gw.y), v0[3] * bfhi(gw.y));
;                     w.z = cvt_pk_bf16(v1[0] * bflo(gw.z), v1[1] * bfhi(gw.z)); w.w = cvt_pk_bf16(v1[2] * bflo(gw.w), v1[3] * bfhi(gw.w));
;                     *(u32x4*)(Y + (size_t)row * DM + col) = w;
	v_lshlrev_b32_e32 v90, 16, v94
	v_and_b32_e32 v91, 0xffff0000, v94
	v_lshlrev_b32_e32 v92, 16, v95
	v_and_b32_e32 v93, 0xffff0000, v95
	v_lshlrev_b32_e32 v94, 16, v96
	v_and_b32_e32 v95, 0xffff0000, v96
	v_lshlrev_b32_e32 v96, 16, v97
	v_and_b32_e32 v97, 0xffff0000, v97
	v_mul_f32_e32 v86, v86, v90
	v_mul_f32_e32 v87, v87, v91
	v_mul_f32_e32 v88, v88, v92
	v_mul_f32_e32 v89, v89, v93
	v_mul_f32_e32 v85, v85, v97
	v_mul_f32_e32 v90, v82, v94
	v_mul_f32_e32 v91, v83, v95
	v_mul_f32_e32 v92, v84, v96
	v_cvt_pk_bf16_f32 v82, v86, v87
	v_cvt_pk_bf16_f32 v83, v88, v89
	v_cvt_pk_bf16_f32 v84, v90, v91
	v_cvt_pk_bf16_f32 v85, v92, v85
	global_load_dwordx4 v[86:89], v[104:105], off nt
	v_lshl_add_u64 v[90:91], v[100:101], 0, v[132:133]
	global_store_dwordx4 v[102:103], v[82:85], off offset:256
	s_waitcnt vmcnt(1)
	s_nop 0
	v_lshlrev_b32_e32 v82, 16, v86
	v_and_b32_e32 v83, 0xffff0000, v86
	v_lshlrev_b32_e32 v84, 16, v87
	v_and_b32_e32 v85, 0xffff0000, v87
	v_lshlrev_b32_e32 v86, 16, v88
	v_and_b32_e32 v87, 0xffff0000, v88
	v_lshlrev_b32_e32 v88, 16, v89
	v_and_b32_e32 v89, 0xffff0000, v89
	v_mul_f32_e32 v78, v78, v82
	v_mul_f32_e32 v79, v79, v83
	v_mul_f32_e32 v80, v80, v84
	v_mul_f32_e32 v81, v81, v85
	v_mul_f32_e32 v77, v77, v89
	v_mul_f32_e32 v82, v74, v86
	v_mul_f32_e32 v83, v75, v87
	v_mul_f32_e32 v84, v76, v88
	v_cvt_pk_bf16_f32 v74, v78, v79
	v_cvt_pk_bf16_f32 v75, v80, v81
	v_cvt_pk_bf16_f32 v76, v82, v83
	v_cvt_pk_bf16_f32 v77, v84, v77
	global_load_dwordx4 v[78:81], v[90:91], off nt
	v_lshlrev_b64 v[86:87], 11, v[98:99]
	v_add_u32_e32 v82, 0x80, v134
	v_lshl_add_u64 v[86:87], s[14:15], 0, v[86:87]
	v_mad_i64_i32 v[84:85], s[26:27], v82, s82, v[136:137]
	v_lshl_add_u64 v[86:87], v[86:87], 0, v[130:131]
	v_lshl_add_u64 v[84:85], v[84:85], 0, s[38:39]
	global_store_dwordx4 v[86:87], v[74:77], off
	v_lshl_add_u64 v[88:89], v[84:85], 0, v[130:131]
	v_ashrrev_i32_e32 v83, 31, v82
	s_waitcnt vmcnt(1)
	v_lshlrev_b32_e32 v74, 16, v78
	v_and_b32_e32 v75, 0xffff0000, v78
	v_lshlrev_b32_e32 v76, 16, v79
	v_and_b32_e32 v77, 0xffff0000, v79
	v_lshlrev_b32_e32 v78, 16, v80
	v_and_b32_e32 v79, 0xffff0000, v80
	v_lshlrev_b32_e32 v80, 16, v81
	v_and_b32_e32 v81, 0xffff0000, v81
	v_mul_f32_e32 v70, v70, v74
	v_mul_f32_e32 v71, v71, v75
	v_mul_f32_e32 v72, v72, v76
	v_mul_f32_e32 v73, v73, v77
	v_mul_f32_e32 v69, v69, v81
	v_mul_f32_e32 v74, v66, v78
	v_mul_f32_e32 v75, v67, v79
	v_mul_f32_e32 v76, v68, v80
	v_cvt_pk_bf16_f32 v66, v70, v71
	v_cvt_pk_bf16_f32 v67, v72, v73
	v_cvt_pk_bf16_f32 v68, v74, v75
	v_cvt_pk_bf16_f32 v69, v76, v69
	global_load_dwordx4 v[70:73], v[88:89], off nt
	v_lshl_add_u64 v[74:75], v[84:85], 0, v[132:133]
	global_store_dwordx4 v[86:87], v[66:69], off offset:256
	s_waitcnt vmcnt(1)
	s_nop 0
	v_lshlrev_b32_e32 v66, 16, v70
	v_and_b32_e32 v67, 0xffff0000, v70
	v_lshlrev_b32_e32 v68, 16, v71
	v_and_b32_e32 v69, 0xffff0000, v71
	v_lshlrev_b32_e32 v70, 16, v72
	v_and_b32_e32 v71, 0xffff0000, v72
	v_lshlrev_b32_e32 v72, 16, v73
	v_and_b32_e32 v73, 0xffff0000, v73
	v_mul_f32_e32 v62, v62, v66
	v_mul_f32_e32 v63, v63, v67
	v_mul_f32_e32 v64, v64, v68
	v_mul_f32_e32 v65, v65, v69
	v_mul_f32_e32 v61, v61, v73
	v_mul_f32_e32 v66, v58, v70
	v_mul_f32_e32 v67, v59, v71
	v_mul_f32_e32 v68, v60, v72
	v_cvt_pk_bf16_f32 v58, v62, v63
	v_cvt_pk_bf16_f32 v59, v64, v65
	v_cvt_pk_bf16_f32 v60, v66, v67
	v_cvt_pk_bf16_f32 v61, v68, v61
	global_load_dwordx4 v[62:65], v[74:75], off nt
	v_lshlrev_b64 v[70:71], 11, v[82:83]
	v_add_u32_e32 v66, 0x90, v134
	v_lshl_add_u64 v[70:71], s[14:15], 0, v[70:71]
	v_mad_i64_i32 v[68:69], s[26:27], v66, s82, v[136:137]
	v_lshl_add_u64 v[70:71], v[70:71], 0, v[130:131]
	v_lshl_add_u64 v[68:69], v[68:69], 0, s[38:39]
	global_store_dwordx4 v[70:71], v[58:61], off
	v_lshl_add_u64 v[72:73], v[68:69], 0, v[130:131]
	v_ashrrev_i32_e32 v67, 31, v66
	s_waitcnt vmcnt(1)
	v_lshlrev_b32_e32 v58, 16, v62
	v_and_b32_e32 v59, 0xffff0000, v62
	v_lshlrev_b32_e32 v60, 16, v63
	v_and_b32_e32 v61, 0xffff0000, v63
	v_lshlrev_b32_e32 v62, 16, v64
	v_and_b32_e32 v63, 0xffff0000, v64
	v_lshlrev_b32_e32 v64, 16, v65
	v_and_b32_e32 v65, 0xffff0000, v65
	v_mul_f32_e32 v54, v54, v58
	v_mul_f32_e32 v55, v55, v59
	v_mul_f32_e32 v56, v56, v60
	v_mul_f32_e32 v57, v57, v61
	v_mul_f32_e32 v53, v53, v65
	v_mul_f32_e32 v58, v50, v62
	v_mul_f32_e32 v59, v51, v63
	v_mul_f32_e32 v60, v52, v64
	v_cvt_pk_bf16_f32 v50, v54, v55
	v_cvt_pk_bf16_f32 v51, v56, v57
	v_cvt_pk_bf16_f32 v52, v58, v59
	v_cvt_pk_bf16_f32 v53, v60, v53
	global_load_dwordx4 v[54:57], v[72:73], off nt
	v_lshl_add_u64 v[58:59], v[68:69], 0, v[132:133]
	global_store_dwordx4 v[70:71], v[50:53], off offset:256
	s_waitcnt vmcnt(1)
; __device__ __forceinline__ unsigned cvt_pk_bf16(float lo, float hi) { unsigned r; asm volatile("v_cvt_pk_bf16_f32 %0, %1, %2" : "=v"(r) : "v"(lo), "v"(hi)); return r; }
; __device__ __forceinline__ float bflo(unsigned w) { return __uint_as_float(w << 16); }
; __device__ __forceinline__ float bfhi(unsigned w) { return __uint_as_float(w & 0xffff0000u); }
;     __device__ __forceinline__ void operator()(f32x4 (&acc)[2][2][4][2], const pg8::Unit& u, int wr, int wc, int fr, int fq, LAS unsigned char*) const {
;     ...
;                 const int row = row0 + ai * 128 + m * 16;
; #pragma unroll
;                 for (int bj = 0; bj < 2; ++bj) {
;                     const int col = col0 + bj * 128;
;                     const u32x4 gw = *(const u32x4*)(gates + (size_t)row * 3072 + 2048 + col);
;                     const f32x4 v0 = acc[ai][bj][m][0], v1 = acc[ai][bj][m][1];
;                     u32x4 w; w.x = cvt_pk_bf16(v0[0] * bflo(gw.x), v0[1] * bfhi(gw.x)); w.y = cvt_pk_bf16(v0[2] * bflo(gw.y), v0[3] * bfhi(gw.y));
;                     w.z = cvt_pk_bf16(v1[0] * bflo(gw.z), v1[1] * bfhi(gw.z)); w.w = cvt_pk_bf16(v1[2] * bflo(gw.w), v1[3] * bfhi(gw.w));
;                     *(u32x4*)(Y + (size_t)row * DM + col) = w;
	s_nop 0
	v_lshlrev_b32_e32 v50, 16, v54
	v_and_b32_e32 v51, 0xffff0000, v54
	v_lshlrev_b32_e32 v52, 16, v55
	v_and_b32_e32 v53, 0xffff0000, v55
	v_lshlrev_b32_e32 v54, 16, v56
	v_and_b32_e32 v55, 0xffff0000, v56
	v_lshlrev_b32_e32 v56, 16, v57
	v_and_b32_e32 v57, 0xffff0000, v57
	v_mul_f32_e32 v46, v46, v50
	v_mul_f32_e32 v47, v47, v51
	v_mul_f32_e32 v48, v48, v52
	v_mul_f32_e32 v49, v49, v53
	v_mul_f32_e32 v45, v45, v57
	v_mul_f32_e32 v50, v42, v54
	v_mul_f32_e32 v51, v43, v55
	v_mul_f32_e32 v52, v44, v56
	v_cvt_pk_bf16_f32 v42, v46, v47
	v_cvt_pk_bf16_f32 v43, v48, v49
	v_cvt_pk_bf16_f32 v44, v50, v51
	v_cvt_pk_bf16_f32 v45, v52, v45
	global_load_dwordx4 v[46:49], v[58:59], off nt
	v_lshlrev_b64 v[54:55], 11, v[66:67]
	v_add_u32_e32 v50, 0xa0, v134
	v_lshl_add_u64 v[54:55], s[14:15], 0, v[54:55]
	v_mad_i64_i32 v[52:53], s[26:27], v50, s82, v[136:137]
	v_lshl_add_u64 v[54:55], v[54:55], 0, v[130:131]
	v_lshl_add_u64 v[52:53], v[52:53], 0, s[38:39]
	global_store_dwordx4 v[54:55], v[42:45], off
	v_lshl_add_u64 v[56:57], v[52:53], 0, v[130:131]
	v_ashrrev_i32_e32 v51, 31, v50
	s_waitcnt vmcnt(1)
	v_lshlrev_b32_e32 v42, 16, v46
	v_and_b32_e32 v43, 0xffff0000, v46
	v_lshlrev_b32_e32 v44, 16, v47
	v_and_b32_e32 v45, 0xffff0000, v47
	v_lshlrev_b32_e32 v46, 16, v48
	v_and_b32_e32 v47, 0xffff0000, v48
	v_lshlrev_b32_e32 v48, 16, v49
	v_and_b32_e32 v49, 0xffff0000, v49
	v_mul_f32_e32 v38, v38, v42
	v_mul_f32_e32 v39, v39, v43
	v_mul_f32_e32 v40, v40, v44
	v_mul_f32_e32 v41, v41, v45
	v_mul_f32_e32 v37, v37, v49
	v_mul_f32_e32 v42, v34, v46
	v_mul_f32_e32 v43, v35, v47
	v_mul_f32_e32 v44, v36, v48
	v_cvt_pk_bf16_f32 v34, v38, v39
	v_cvt_pk_bf16_f32 v35, v40, v41
	v_cvt_pk_bf16_f32 v36, v42, v43
	v_cvt_pk_bf16_f32 v37, v44, v37
	global_load_dwordx4 v[38:41], v[56:57], off nt
	v_lshl_add_u64 v[42:43], v[52:53], 0, v[132:133]
	global_store_dwordx4 v[54:55], v[34:37], off offset:256
	s_waitcnt vmcnt(1)
	s_nop 0
	v_lshlrev_b32_e32 v34, 16, v38
	v_and_b32_e32 v35, 0xffff0000, v38
	v_lshlrev_b32_e32 v36, 16, v39
	v_and_b32_e32 v37, 0xffff0000, v39
	v_lshlrev_b32_e32 v38, 16, v40
	v_and_b32_e32 v39, 0xffff0000, v40
	v_lshlrev_b32_e32 v40, 16, v41
	v_and_b32_e32 v41, 0xffff0000, v41
	v_mul_f32_e32 v30, v30, v34
	v_mul_f32_e32 v31, v31, v35
	v_mul_f32_e32 v32, v32, v36
	v_mul_f32_e32 v33, v33, v37
	v_mul_f32_e32 v29, v29, v41
	v_mul_f32_e32 v34, v26, v38
	v_mul_f32_e32 v35, v27, v39
	v_mul_f32_e32 v36, v28, v40
	v_cvt_pk_bf16_f32 v26, v30, v31
	v_cvt_pk_bf16_f32 v27, v32, v33
	v_cvt_pk_bf16_f32 v28, v34, v35
	v_cvt_pk_bf16_f32 v29, v36, v29
	global_load_dwordx4 v[30:33], v[42:43], off nt
	v_lshlrev_b64 v[38:39], 11, v[50:51]
	v_add_u32_e32 v34, 0xb0, v134
	v_lshl_add_u64 v[38:39], s[14:15], 0, v[38:39]
	v_mad_i64_i32 v[36:37], s[26:27], v34, s82, v[136:137]
	v_lshl_add_u64 v[38:39], v[38:39], 0, v[130:131]
	v_lshl_add_u64 v[36:37], v[36:37], 0, s[38:39]
	global_store_dwordx4 v[38:39], v[26:29], off
	v_lshl_add_u64 v[40:41], v[36:37], 0, v[130:131]
	v_ashrrev_i32_e32 v35, 31, v34
	s_waitcnt vmcnt(1)
	v_lshlrev_b32_e32 v26, 16, v30
	v_and_b32_e32 v27, 0xffff0000, v30
	v_lshlrev_b32_e32 v28, 16, v31
	v_and_b32_e32 v29, 0xffff0000, v31
	v_lshlrev_b32_e32 v30, 16, v32
	v_and_b32_e32 v31, 0xffff0000, v32
	v_lshlrev_b32_e32 v32, 16, v33
	v_and_b32_e32 v33, 0xffff0000, v33
	v_mul_f32_e32 v22, v22, v26
	v_mul_f32_e32 v23, v23, v27
	v_mul_f32_e32 v24, v24, v28
	v_mul_f32_e32 v25, v25, v29
	v_mul_f32_e32 v21, v21, v33
	v_mul_f32_e32 v26, v18, v30
	v_mul_f32_e32 v27, v19, v31
	v_mul_f32_e32 v28, v20, v32
	v_cvt_pk_bf16_f32 v18, v22, v23
	v_cvt_pk_bf16_f32 v19, v24, v25
	v_cvt_pk_bf16_f32 v20, v26, v27
	v_cvt_pk_bf16_f32 v21, v28, v21
	global_load_dwordx4 v[22:25], v[40:41], off nt
	v_lshl_add_u64 v[26:27], v[36:37], 0, v[132:133]
	global_store_dwordx4 v[38:39], v[18:21], off offset:256
	s_waitcnt vmcnt(1)
	s_nop 0
	v_lshlrev_b32_e32 v18, 16, v22
	v_and_b32_e32 v19, 0xffff0000, v22
	v_lshlrev_b32_e32 v20, 16, v23
	v_and_b32_e32 v21, 0xffff0000, v23
	v_lshlrev_b32_e32 v22, 16, v24
	v_and_b32_e32 v23, 0xffff0000, v24
	v_lshlrev_b32_e32 v24, 16, v25
	v_and_b32_e32 v25, 0xffff0000, v25
	v_mul_f32_e32 v14, v14, v18
	v_mul_f32_e32 v15, v15, v19
	v_mul_f32_e32 v16, v16, v20
	v_mul_f32_e32 v17, v17, v21
	v_mul_f32_e32 v13, v13, v25
	v_mul_f32_e32 v18, v10, v22
	v_mul_f32_e32 v19, v11, v23
	v_mul_f32_e32 v20, v12, v24
	v_cvt_pk_bf16_f32 v10, v14, v15
	v_cvt_pk_bf16_f32 v11, v16, v17
	v_cvt_pk_bf16_f32 v12, v18, v19
	v_cvt_pk_bf16_f32 v13, v20, v13
	global_load_dwordx4 v[14:17], v[26:27], off nt
	v_lshlrev_b64 v[18:19], 11, v[34:35]
	v_lshl_add_u64 v[18:19], s[14:15], 0, v[18:19]
	v_lshl_add_u64 v[18:19], v[18:19], 0, v[130:131]
	global_store_dwordx4 v[18:19], v[10:13], off
	s_waitcnt vmcnt(1)
	s_nop 0
	v_lshlrev_b32_e32 v10, 16, v14
	v_and_b32_e32 v11, 0xffff0000, v14
	v_lshlrev_b32_e32 v12, 16, v15
	v_and_b32_e32 v13, 0xffff0000, v15
	v_lshlrev_b32_e32 v14, 16, v16
	v_and_b32_e32 v15, 0xffff0000, v16
	v_lshlrev_b32_e32 v16, 16, v17
	v_and_b32_e32 v17, 0xffff0000, v17
	v_mul_f32_e32 v5, v5, v17
	v_mul_f32_e32 v6, v6, v10
	v_mul_f32_e32 v7, v7, v11
	v_mul_f32_e32 v8, v8, v12
	v_mul_f32_e32 v9, v9, v13
	v_mul_f32_e32 v10, v2, v14
	v_mul_f32_e32 v11, v3, v15
	v_mul_f32_e32 v12, v4, v16
	v_cvt_pk_bf16_f32 v2, v6, v7
	v_cvt_pk_bf16_f32 v3, v8, v9
	v_cvt_pk_bf16_f32 v4, v10, v11
	v_cvt_pk_bf16_f32 v5, v12, v5
	global_store_dwordx4 v[18:19], v[2:5], off offset:256
	s_cbranch_vccnz .LBB0_95
	s_andn2_b64 vcc, exec, s[6:7]
	s_cbranch_vccnz .LBB0_94
	s_barrier
	s_branch .LBB0_94

; __device__ __forceinline__ unsigned cvt_pk_bf16(float lo, float hi) { unsigned r; asm volatile("v_cvt_pk_bf16_f32 %0, %1, %2" : "=v"(r) : "v"(lo), "v"(hi)); return r; }
;     __device__ __forceinline__ void operator()(const f32x4 (&acc)[2][2][4][2], const pg8::Unit& u, int wr, int wc, int fr, int fq, LAS unsigned char*) const {
;     ...
;         for (int ai = 0; ai < 2; ++ai)
; #pragma unroll
;             for (int m = 0; m < 4; ++m) {
;                 const int row = row0 + ai * 128 + m * 16; const size_t off = (size_t)row * DM + col0; float q = 0.f;
; #pragma unroll
;                 for (int bj = 0; bj < 2; ++bj)
; #pragma unroll
;                     for (int n = 0; n < 2; ++n) { const size_t o = off + bj * 128 + n * 16; const f32x4 xv = *(const f32x4*)(xin + o) + acc[ai][bj][m][n]; *(f32x4*)(xout + o) = xv;
;                         q += (xv[0] * xv[0] + xv[1] * xv[1]) + (xv[2] * xv[2] + xv[3] * xv[3]);
;                         u32x2 w; w.x = cvt_pk_bf16(xv[0], xv[1]); w.y = cvt_pk_bf16(xv[2], xv[3]); *(u32x2*)(xb + o) = w; }
;                 q += __shfl_xor(q, 16); q += __shfl_xor(q, 32);
;                 if (fq == 0) ssq[(size_t)row * 16 + u.pn * 4 + wc] = q;
.LBB0_421:
	v_lshl_add_u32 v136, s68, 8, v142
	v_lshl_or_b32 v137, s28, 8, v144
	s_lshl_b32 s50, s28, 4
	s_lshl_b32 s51, s59, 2
	s_add_u32 s50, s50, s51
	v_lshl_add_u32 v139, v136, 10, v137
	v_lshl_add_u32 v140, v136, 6, s50
	v_lshlrev_b32_e32 v138, 2, v139
	v_lshlrev_b32_e32 v139, 1, v139
	v_xor_b32_e32 v141, 16, v187
	v_xor_b32_e32 v172, 32, v187
	v_lshlrev_b32_e32 v141, 2, v141
	v_lshlrev_b32_e32 v172, 2, v172
	global_load_dwordx4 v[198:201], v138, s[12:13] nt
	global_load_dwordx4 v[202:205], v138, s[12:13] offset:64 nt
	global_load_dwordx4 v[206:209], v138, s[12:13] offset:512 nt
	global_load_dwordx4 v[210:213], v138, s[12:13] offset:576 nt
	v_add_u32_e32 v173, 0x10000, v138
	global_load_dwordx4 v[214:217], v173, s[12:13] nt
	global_load_dwordx4 v[218:221], v173, s[12:13] offset:64 nt
	global_load_dwordx4 v[222:225], v173, s[12:13] offset:512 nt
	global_load_dwordx4 v[226:229], v173, s[12:13] offset:576 nt
	v_add_u32_e32 v173, 0x20000, v138
	global_load_dwordx4 v[156:159], v173, s[12:13] nt
	global_load_dwordx4 v[160:163], v173, s[12:13] offset:64 nt
	global_load_dwordx4 v[164:167], v173, s[12:13] offset:512 nt
	global_load_dwordx4 v[168:171], v173, s[12:13] offset:576 nt
	v_mov_b32_e32 v174, v138
	v_mov_b32_e32 v175, v139
	v_mov_b32_e32 v176, v140
	s_waitcnt vmcnt(11)
	v_pk_add_f32 v[200:201], v[128:129], v[200:201]
	v_pk_add_f32 v[198:199], v[126:127], v[198:199]
	global_store_dwordx4 v174, v[198:201], s[84:85]
	v_mul_f32_e32 v178, v201, v201
	v_mul_f32_e32 v177, v199, v199
	v_fmac_f32_e32 v177, v198, v198
	v_fmac_f32_e32 v178, v200, v200
	v_cvt_pk_bf16_f32 v180, v198, v199
	v_cvt_pk_bf16_f32 v181, v200, v201
	v_add_f32_e32 v179, v177, v178
	global_store_dwordx2 v175, v[180:181], s[18:19]
	s_waitcnt vmcnt(12)
	v_pk_add_f32 v[204:205], v[124:125], v[204:205]
	v_pk_add_f32 v[202:203], v[122:123], v[202:203]
	global_store_dwordx4 v174, v[202:205], s[84:85] offset:64
	v_mul_f32_e32 v178, v205, v205
	v_mul_f32_e32 v177, v203, v203
	v_fmac_f32_e32 v177, v202, v202
	v_fmac_f32_e32 v178, v204, v204
	v_cvt_pk_bf16_f32 v182, v202, v203
	v_cvt_pk_bf16_f32 v183, v204, v205
	v_add_f32_e32 v177, v177, v178
	v_add_f32_e32 v179, v179, v177
	global_store_dwordx2 v175, v[182:183], s[18:19] offset:32
	s_waitcnt vmcnt(13)
	v_pk_add_f32 v[208:209], v[120:121], v[208:209]
	v_pk_add_f32 v[206:207], v[118:119], v[206:207]
	global_store_dwordx4 v174, v[206:209], s[84:85] offset:512
	v_mul_f32_e32 v178, v209, v209
	v_mul_f32_e32 v177, v207, v207
	v_fmac_f32_e32 v177, v206, v206
	v_fmac_f32_e32 v178, v208, v208
	v_cvt_pk_bf16_f32 v180, v206, v207
	v_cvt_pk_bf16_f32 v181, v208, v209
	v_add_f32_e32 v177, v177, v178
	v_add_f32_e32 v179, v179, v177
	global_store_dwordx2 v175, v[180:181], s[18:19] offset:256
	s_waitcnt vmcnt(14)
	v_pk_add_f32 v[212:213], v[116:117], v[212:213]
	v_pk_add_f32 v[210:211], v[114:115], v[210:211]
	global_store_dwordx4 v174, v[210:213], s[84:85] offset:576
	v_mul_f32_e32 v178, v213, v213
	v_mul_f32_e32 v177, v211, v211
	v_fmac_f32_e32 v177, v210, v210
	v_fmac_f32_e32 v178, v212, v212
	v_cvt_pk_bf16_f32 v182, v210, v211
	v_cvt_pk_bf16_f32 v183, v212, v213
	v_add_f32_e32 v177, v177, v178
	v_add_f32_e32 v179, v179, v177
	global_store_dwordx2 v175, v[182:183], s[18:19] offset:288
	ds_bpermute_b32 v177, v141, v179
	s_waitcnt lgkmcnt(0)
	v_add_f32_e32 v179, v179, v177
	ds_bpermute_b32 v178, v172, v179
	s_waitcnt lgkmcnt(0)
	v_add_f32_e32 v179, v179, v178
	s_and_saveexec_b64 s[52:53], s[4:5]
	global_store_dword v176, v179, s[14:15]
	s_mov_b64 exec, s[52:53]
	v_add_u32_e32 v173, 0x30000, v138
	global_load_dwordx4 v[198:201], v173, s[12:13] nt
	global_load_dwordx4 v[202:205], v173, s[12:13] offset:64 nt
	global_load_dwordx4 v[206:209], v173, s[12:13] offset:512 nt
	global_load_dwordx4 v[210:213], v173, s[12:13] offset:576 nt
	v_add_u32_e32 v174, 0x10000, v138
	v_add_u32_e32 v175, 0x8000, v139
	v_add_u32_e32 v176, 0x400, v140
	s_waitcnt vmcnt(20)
	v_pk_add_f32 v[216:217], v[112:113], v[216:217]
	v_pk_add_f32 v[214:215], v[110:111], v[214:215]
	global_store_dwordx4 v174, v[214:217], s[84:85]
	v_mul_f32_e32 v178, v217, v217
	v_mul_f32_e32 v177, v215, v215
	v_fmac_f32_e32 v177, v214, v214
	v_fmac_f32_e32 v178, v216, v216
	v_cvt_pk_bf16_f32 v180, v214, v215
	v_cvt_pk_bf16_f32 v181, v216, v217
	v_add_f32_e32 v179, v177, v178
	global_store_dwordx2 v175, v[180:181], s[18:19]
	s_waitcnt vmcnt(21)
	v_pk_add_f32 v[220:221], v[108:109], v[220:221]
	v_pk_add_f32 v[218:219], v[106:107], v[218:219]
	global_store_dwordx4 v174, v[218:221], s[84:85] offset:64
	v_mul_f32_e32 v178, v221, v221
	v_mul_f32_e32 v177, v219, v219
	v_fmac_f32_e32 v177, v218, v218
	v_fmac_f32_e32 v178, v220, v220
	v_cvt_pk_bf16_f32 v182, v218, v219
	v_cvt_pk_bf16_f32 v183, v220, v221
	v_add_f32_e32 v177, v177, v178
	v_add_f32_e32 v179, v179, v177
	global_store_dwordx2 v175, v[182:183], s[18:19] offset:32
	s_waitcnt vmcnt(22)
	v_pk_add_f32 v[224:225], v[104:105], v[224:225]
	v_pk_add_f32 v[222:223], v[102:103], v[222:223]
	global_store_dwordx4 v174, v[222:225], s[84:85] offset:512
	v_mul_f32_e32 v178, v225, v225
	v_mul_f32_e32 v177, v223, v223
	v_fmac_f32_e32 v177, v222, v222
	v_fmac_f32_e32 v178, v224, v224
	v_cvt_pk_bf16_f32 v180, v222, v223
	v_cvt_pk_bf16_f32 v181, v224, v225
	v_add_f32_e32 v177, v177, v178
	v_add_f32_e32 v179, v179, v177
	global_store_dwordx2 v175, v[180:181], s[18:19] offset:256
	s_waitcnt vmcnt(23)
	v_pk_add_f32 v[228:229], v[100:101], v[228:229]
	v_pk_add_f32 v[226:227], v[98:99], v[226:227]
	global_store_dwordx4 v174, v[226:229], s[84:85] offset:576
	v_mul_f32_e32 v178, v229, v229
	v_mul_f32_e32 v177, v227, v227
	v_fmac_f32_e32 v177, v226, v226
	v_fmac_f32_e32 v178, v228, v228
	v_cvt_pk_bf16_f32 v182, v226, v227
	v_cvt_pk_bf16_f32 v183, v228, v229
	v_add_f32_e32 v177, v177, v178
	v_add_f32_e32 v179, v179, v177
	global_store_dwordx2 v175, v[182:183], s[18:19] offset:288
	ds_bpermute_b32 v177, v141, v179
	s_waitcnt lgkmcnt(0)
; __device__ __forceinline__ unsigned cvt_pk_bf16(float lo, float hi) { unsigned r; asm volatile("v_cvt_pk_bf16_f32 %0, %1, %2" : "=v"(r) : "v"(lo), "v"(hi)); return r; }
;     __device__ __forceinline__ void operator()(const f32x4 (&acc)[2][2][4][2], const pg8::Unit& u, int wr, int wc, int fr, int fq, LAS unsigned char*) const {
;     ...
;         for (int ai = 0; ai < 2; ++ai)
; #pragma unroll
;             for (int m = 0; m < 4; ++m) {
;                 const int row = row0 + ai * 128 + m * 16; const size_t off = (size_t)row * DM + col0; float q = 0.f;
; #pragma unroll
;                 for (int bj = 0; bj < 2; ++bj)
; #pragma unroll
;                     for (int n = 0; n < 2; ++n) { const size_t o = off + bj * 128 + n * 16; const f32x4 xv = *(const f32x4*)(xin + o) + acc[ai][bj][m][n]; *(f32x4*)(xout + o) = xv;
;                         q += (xv[0] * xv[0] + xv[1] * xv[1]) + (xv[2] * xv[2] + xv[3] * xv[3]);
;                         u32x2 w; w.x = cvt_pk_bf16(xv[0], xv[1]); w.y = cvt_pk_bf16(xv[2], xv[3]); *(u32x2*)(xb + o) = w; }
;                 q += __shfl_xor(q, 16); q += __shfl_xor(q, 32);
;                 if (fq == 0) ssq[(size_t)row * 16 + u.pn * 4 + wc] = q;
	v_add_f32_e32 v179, v179, v177
	ds_bpermute_b32 v178, v172, v179
	s_waitcnt lgkmcnt(0)
	v_add_f32_e32 v179, v179, v178
	s_and_saveexec_b64 s[52:53], s[4:5]
	global_store_dword v176, v179, s[14:15]
	s_mov_b64 exec, s[52:53]
	v_add_u32_e32 v173, 0x80000, v138
	global_load_dwordx4 v[214:217], v173, s[12:13] nt
	global_load_dwordx4 v[218:221], v173, s[12:13] offset:64 nt
	global_load_dwordx4 v[222:225], v173, s[12:13] offset:512 nt
	global_load_dwordx4 v[226:229], v173, s[12:13] offset:576 nt
	v_add_u32_e32 v174, 0x20000, v138
	v_add_u32_e32 v175, 0x10000, v139
	v_add_u32_e32 v176, 0x800, v140
	s_waitcnt vmcnt(29)
	v_pk_add_f32 v[158:159], v[96:97], v[158:159]
	v_pk_add_f32 v[156:157], v[94:95], v[156:157]
	global_store_dwordx4 v174, v[156:159], s[84:85]
	v_mul_f32_e32 v178, v159, v159
	v_mul_f32_e32 v177, v157, v157
	v_fmac_f32_e32 v177, v156, v156
	v_fmac_f32_e32 v178, v158, v158
	v_cvt_pk_bf16_f32 v180, v156, v157
	v_cvt_pk_bf16_f32 v181, v158, v159
	v_add_f32_e32 v179, v177, v178
	global_store_dwordx2 v175, v[180:181], s[18:19]
	s_waitcnt vmcnt(30)
	v_pk_add_f32 v[162:163], v[92:93], v[162:163]
	v_pk_add_f32 v[160:161], v[90:91], v[160:161]
	global_store_dwordx4 v174, v[160:163], s[84:85] offset:64
	v_mul_f32_e32 v178, v163, v163
	v_mul_f32_e32 v177, v161, v161
	v_fmac_f32_e32 v177, v160, v160
	v_fmac_f32_e32 v178, v162, v162
	v_cvt_pk_bf16_f32 v182, v160, v161
	v_cvt_pk_bf16_f32 v183, v162, v163
	v_add_f32_e32 v177, v177, v178
	v_add_f32_e32 v179, v179, v177
	global_store_dwordx2 v175, v[182:183], s[18:19] offset:32
	s_waitcnt vmcnt(31)
	v_pk_add_f32 v[166:167], v[88:89], v[166:167]
	v_pk_add_f32 v[164:165], v[86:87], v[164:165]
	global_store_dwordx4 v174, v[164:167], s[84:85] offset:512
	v_mul_f32_e32 v178, v167, v167
	v_mul_f32_e32 v177, v165, v165
	v_fmac_f32_e32 v177, v164, v164
	v_fmac_f32_e32 v178, v166, v166
	v_cvt_pk_bf16_f32 v180, v164, v165
	v_cvt_pk_bf16_f32 v181, v166, v167
	v_add_f32_e32 v177, v177, v178
	v_add_f32_e32 v179, v179, v177
	global_store_dwordx2 v175, v[180:181], s[18:19] offset:256
	s_waitcnt vmcnt(32)
	v_pk_add_f32 v[170:171], v[84:85], v[170:171]
	v_pk_add_f32 v[168:169], v[82:83], v[168:169]
	global_store_dwordx4 v174, v[168:171], s[84:85] offset:576
	v_mul_f32_e32 v178, v171, v171
	v_mul_f32_e32 v177, v169, v169
	v_fmac_f32_e32 v177, v168, v168
	v_fmac_f32_e32 v178, v170, v170
	v_cvt_pk_bf16_f32 v182, v168, v169
	v_cvt_pk_bf16_f32 v183, v170, v171
	v_add_f32_e32 v177, v177, v178
	v_add_f32_e32 v179, v179, v177
	global_store_dwordx2 v175, v[182:183], s[18:19] offset:288
	ds_bpermute_b32 v177, v141, v179
	s_waitcnt lgkmcnt(0)
	v_add_f32_e32 v179, v179, v177
	ds_bpermute_b32 v178, v172, v179
	s_waitcnt lgkmcnt(0)
	v_add_f32_e32 v179, v179, v178
	s_and_saveexec_b64 s[52:53], s[4:5]
	global_store_dword v176, v179, s[14:15]
	s_mov_b64 exec, s[52:53]
	v_add_u32_e32 v173, 0x90000, v138
	global_load_dwordx4 v[156:159], v173, s[12:13] nt
	global_load_dwordx4 v[160:163], v173, s[12:13] offset:64 nt
	global_load_dwordx4 v[164:167], v173, s[12:13] offset:512 nt
	global_load_dwordx4 v[168:171], v173, s[12:13] offset:576 nt
	v_add_u32_e32 v174, 0x30000, v138
	v_add_u32_e32 v175, 0x18000, v139
	v_add_u32_e32 v176, 0xc00, v140
	s_waitcnt vmcnt(29)
	v_pk_add_f32 v[200:201], v[80:81], v[200:201]
	v_pk_add_f32 v[198:199], v[78:79], v[198:199]
	global_store_dwordx4 v174, v[198:201], s[84:85]
	v_mul_f32_e32 v178, v201, v201
	v_mul_f32_e32 v177, v199, v199
	v_fmac_f32_e32 v177, v198, v198
	v_fmac_f32_e32 v178, v200, v200
	v_cvt_pk_bf16_f32 v180, v198, v199
	v_cvt_pk_bf16_f32 v181, v200, v201
	v_add_f32_e32 v179, v177, v178
	global_store_dwordx2 v175, v[180:181], s[18:19]
	s_waitcnt vmcnt(30)
	v_pk_add_f32 v[204:205], v[76:77], v[204:205]
	v_pk_add_f32 v[202:203], v[74:75], v[202:203]
	global_store_dwordx4 v174, v[202:205], s[84:85] offset:64
	v_mul_f32_e32 v178, v205, v205
	v_mul_f32_e32 v177, v203, v203
	v_fmac_f32_e32 v177, v202, v202
	v_fmac_f32_e32 v178, v204, v204
	v_cvt_pk_bf16_f32 v182, v202, v203
	v_cvt_pk_bf16_f32 v183, v204, v205
	v_add_f32_e32 v177, v177, v178
	v_add_f32_e32 v179, v179, v177
	global_store_dwordx2 v175, v[182:183], s[18:19] offset:32
	s_waitcnt vmcnt(31)
	v_pk_add_f32 v[208:209], v[72:73], v[208:209]
	v_pk_add_f32 v[206:207], v[70:71], v[206:207]
	global_store_dwordx4 v174, v[206:209], s[84:85] offset:512
	v_mul_f32_e32 v178, v209, v209
	v_mul_f32_e32 v177, v207, v207
	v_fmac_f32_e32 v177, v206, v206
	v_fmac_f32_e32 v178, v208, v208
	v_cvt_pk_bf16_f32 v180, v206, v207
	v_cvt_pk_bf16_f32 v181, v208, v209
	v_add_f32_e32 v177, v177, v178
	v_add_f32_e32 v179, v179, v177
	global_store_dwordx2 v175, v[180:181], s[18:19] offset:256
	s_waitcnt vmcnt(32)
	v_pk_add_f32 v[212:213], v[68:69], v[212:213]
	v_pk_add_f32 v[210:211], v[66:67], v[210:211]
	global_store_dwordx4 v174, v[210:213], s[84:85] offset:576
	v_mul_f32_e32 v178, v213, v213
	v_mul_f32_e32 v177, v211, v211
	v_fmac_f32_e32 v177, v210, v210
	v_fmac_f32_e32 v178, v212, v212
	v_cvt_pk_bf16_f32 v182, v210, v211
	v_cvt_pk_bf16_f32 v183, v212, v213
	v_add_f32_e32 v177, v177, v178
	v_add_f32_e32 v179, v179, v177
	global_store_dwordx2 v175, v[182:183], s[18:19] offset:288
	ds_bpermute_b32 v177, v141, v179
	s_waitcnt lgkmcnt(0)
	v_add_f32_e32 v179, v179, v177
	ds_bpermute_b32 v178, v172, v179
	s_waitcnt lgkmcnt(0)
	v_add_f32_e32 v179, v179, v178
	s_and_saveexec_b64 s[52:53], s[4:5]
	global_store_dword v176, v179, s[14:15]
	s_mov_b64 exec, s[52:53]
	v_add_u32_e32 v173, 0xa0000, v138
	global_load_dwordx4 v[198:201], v173, s[12:13] nt
	global_load_dwordx4 v[202:205], v173, s[12:13] offset:64 nt
	global_load_dwordx4 v[206:209], v173, s[12:13] offset:512 nt
	global_load_dwordx4 v[210:213], v173, s[12:13] offset:576 nt
	v_add_u32_e32 v174, 0x80000, v138
	v_add_u32_e32 v175, 0x40000, v139
	v_add_u32_e32 v176, 0x2000, v140
	s_waitcnt vmcnt(29)
; __device__ __forceinline__ unsigned cvt_pk_bf16(float lo, float hi) { unsigned r; asm volatile("v_cvt_pk_bf16_f32 %0, %1, %2" : "=v"(r) : "v"(lo), "v"(hi)); return r; }
;     __device__ __forceinline__ void operator()(const f32x4 (&acc)[2][2][4][2], const pg8::Unit& u, int wr, int wc, int fr, int fq, LAS unsigned char*) const {
;     ...
;         for (int ai = 0; ai < 2; ++ai)
; #pragma unroll
;             for (int m = 0; m < 4; ++m) {
;                 const int row = row0 + ai * 128 + m * 16; const size_t off = (size_t)row * DM + col0; float q = 0.f;
; #pragma unroll
;                 for (int bj = 0; bj < 2; ++bj)
; #pragma unroll
;                     for (int n = 0; n < 2; ++n) { const size_t o = off + bj * 128 + n * 16; const f32x4 xv = *(const f32x4*)(xin + o) + acc[ai][bj][m][n]; *(f32x4*)(xout + o) = xv;
;                         q += (xv[0] * xv[0] + xv[1] * xv[1]) + (xv[2] * xv[2] + xv[3] * xv[3]);
;                         u32x2 w; w.x = cvt_pk_bf16(xv[0], xv[1]); w.y = cvt_pk_bf16(xv[2], xv[3]); *(u32x2*)(xb + o) = w; }
;                 q += __shfl_xor(q, 16); q += __shfl_xor(q, 32);
;                 if (fq == 0) ssq[(size_t)row * 16 + u.pn * 4 + wc] = q;
	v_pk_add_f32 v[216:217], v[64:65], v[216:217]
	v_pk_add_f32 v[214:215], v[62:63], v[214:215]
	global_store_dwordx4 v174, v[214:217], s[84:85]
	v_mul_f32_e32 v178, v217, v217
	v_mul_f32_e32 v177, v215, v215
	v_fmac_f32_e32 v177, v214, v214
	v_fmac_f32_e32 v178, v216, v216
	v_cvt_pk_bf16_f32 v180, v214, v215
	v_cvt_pk_bf16_f32 v181, v216, v217
	v_add_f32_e32 v179, v177, v178
	global_store_dwordx2 v175, v[180:181], s[18:19]
	s_waitcnt vmcnt(30)
	v_pk_add_f32 v[220:221], v[60:61], v[220:221]
	v_pk_add_f32 v[218:219], v[58:59], v[218:219]
	global_store_dwordx4 v174, v[218:221], s[84:85] offset:64
	v_mul_f32_e32 v178, v221, v221
	v_mul_f32_e32 v177, v219, v219
	v_fmac_f32_e32 v177, v218, v218
	v_fmac_f32_e32 v178, v220, v220
	v_cvt_pk_bf16_f32 v182, v218, v219
	v_cvt_pk_bf16_f32 v183, v220, v221
	v_add_f32_e32 v177, v177, v178
	v_add_f32_e32 v179, v179, v177
	global_store_dwordx2 v175, v[182:183], s[18:19] offset:32
	s_waitcnt vmcnt(31)
	v_pk_add_f32 v[224:225], v[56:57], v[224:225]
	v_pk_add_f32 v[222:223], v[54:55], v[222:223]
	global_store_dwordx4 v174, v[222:225], s[84:85] offset:512
	v_mul_f32_e32 v178, v225, v225
	v_mul_f32_e32 v177, v223, v223
	v_fmac_f32_e32 v177, v222, v222
	v_fmac_f32_e32 v178, v224, v224
	v_cvt_pk_bf16_f32 v180, v222, v223
	v_cvt_pk_bf16_f32 v181, v224, v225
	v_add_f32_e32 v177, v177, v178
	v_add_f32_e32 v179, v179, v177
	global_store_dwordx2 v175, v[180:181], s[18:19] offset:256
	s_waitcnt vmcnt(32)
	v_pk_add_f32 v[228:229], v[52:53], v[228:229]
	v_pk_add_f32 v[226:227], v[50:51], v[226:227]
	global_store_dwordx4 v174, v[226:229], s[84:85] offset:576
	v_mul_f32_e32 v178, v229, v229
	v_mul_f32_e32 v177, v227, v227
	v_fmac_f32_e32 v177, v226, v226
	v_fmac_f32_e32 v178, v228, v228
	v_cvt_pk_bf16_f32 v182, v226, v227
	v_cvt_pk_bf16_f32 v183, v228, v229
	v_add_f32_e32 v177, v177, v178
	v_add_f32_e32 v179, v179, v177
	global_store_dwordx2 v175, v[182:183], s[18:19] offset:288
	ds_bpermute_b32 v177, v141, v179
	s_waitcnt lgkmcnt(0)
	v_add_f32_e32 v179, v179, v177
	ds_bpermute_b32 v178, v172, v179
	s_waitcnt lgkmcnt(0)
	v_add_f32_e32 v179, v179, v178
	s_and_saveexec_b64 s[52:53], s[4:5]
	global_store_dword v176, v179, s[14:15]
	s_mov_b64 exec, s[52:53]
	v_add_u32_e32 v173, 0xb0000, v138
	global_load_dwordx4 v[214:217], v173, s[12:13] nt
	global_load_dwordx4 v[218:221], v173, s[12:13] offset:64 nt
	global_load_dwordx4 v[222:225], v173, s[12:13] offset:512 nt
	global_load_dwordx4 v[226:229], v173, s[12:13] offset:576 nt
	v_add_u32_e32 v174, 0x90000, v138
	v_add_u32_e32 v175, 0x48000, v139
	v_add_u32_e32 v176, 0x2400, v140
	s_waitcnt vmcnt(29)
	v_pk_add_f32 v[158:159], v[48:49], v[158:159]
	v_pk_add_f32 v[156:157], v[46:47], v[156:157]
	global_store_dwordx4 v174, v[156:159], s[84:85]
	v_mul_f32_e32 v178, v159, v159
	v_mul_f32_e32 v177, v157, v157
	v_fmac_f32_e32 v177, v156, v156
	v_fmac_f32_e32 v178, v158, v158
	v_cvt_pk_bf16_f32 v180, v156, v157
	v_cvt_pk_bf16_f32 v181, v158, v159
	v_add_f32_e32 v179, v177, v178
	global_store_dwordx2 v175, v[180:181], s[18:19]
	s_waitcnt vmcnt(30)
	v_pk_add_f32 v[162:163], v[44:45], v[162:163]
	v_pk_add_f32 v[160:161], v[42:43], v[160:161]
	global_store_dwordx4 v174, v[160:163], s[84:85] offset:64
	v_mul_f32_e32 v178, v163, v163
	v_mul_f32_e32 v177, v161, v161
	v_fmac_f32_e32 v177, v160, v160
	v_fmac_f32_e32 v178, v162, v162
	v_cvt_pk_bf16_f32 v182, v160, v161
	v_cvt_pk_bf16_f32 v183, v162, v163
	v_add_f32_e32 v177, v177, v178
	v_add_f32_e32 v179, v179, v177
	global_store_dwordx2 v175, v[182:183], s[18:19] offset:32
	s_waitcnt vmcnt(31)
	v_pk_add_f32 v[166:167], v[40:41], v[166:167]
	v_pk_add_f32 v[164:165], v[38:39], v[164:165]
	global_store_dwordx4 v174, v[164:167], s[84:85] offset:512
	v_mul_f32_e32 v178, v167, v167
	v_mul_f32_e32 v177, v165, v165
	v_fmac_f32_e32 v177, v164, v164
	v_fmac_f32_e32 v178, v166, v166
	v_cvt_pk_bf16_f32 v180, v164, v165
	v_cvt_pk_bf16_f32 v181, v166, v167
	v_add_f32_e32 v177, v177, v178
	v_add_f32_e32 v179, v179, v177
	global_store_dwordx2 v175, v[180:181], s[18:19] offset:256
	s_waitcnt vmcnt(32)
	v_pk_add_f32 v[170:171], v[36:37], v[170:171]
	v_pk_add_f32 v[168:169], v[34:35], v[168:169]
	global_store_dwordx4 v174, v[168:171], s[84:85] offset:576
	v_mul_f32_e32 v178, v171, v171
	v_mul_f32_e32 v177, v169, v169
	v_fmac_f32_e32 v177, v168, v168
	v_fmac_f32_e32 v178, v170, v170
	v_cvt_pk_bf16_f32 v182, v168, v169
	v_cvt_pk_bf16_f32 v183, v170, v171
	v_add_f32_e32 v177, v177, v178
	v_add_f32_e32 v179, v179, v177
	global_store_dwordx2 v175, v[182:183], s[18:19] offset:288
	ds_bpermute_b32 v177, v141, v179
	s_waitcnt lgkmcnt(0)
	v_add_f32_e32 v179, v179, v177
	ds_bpermute_b32 v178, v172, v179
	s_waitcnt lgkmcnt(0)
	v_add_f32_e32 v179, v179, v178
	s_and_saveexec_b64 s[52:53], s[4:5]
	global_store_dword v176, v179, s[14:15]
	s_mov_b64 exec, s[52:53]
	v_add_u32_e32 v174, 0xa0000, v138
	v_add_u32_e32 v175, 0x50000, v139
	v_add_u32_e32 v176, 0x2800, v140
	s_waitcnt vmcnt(25)
; __device__ __forceinline__ unsigned cvt_pk_bf16(float lo, float hi) { unsigned r; asm volatile("v_cvt_pk_bf16_f32 %0, %1, %2" : "=v"(r) : "v"(lo), "v"(hi)); return r; }
;     __device__ __forceinline__ void operator()(const f32x4 (&acc)[2][2][4][2], const pg8::Unit& u, int wr, int wc, int fr, int fq, LAS unsigned char*) const {
;     ...
;         for (int ai = 0; ai < 2; ++ai)
; #pragma unroll
;             for (int m = 0; m < 4; ++m) {
;                 const int row = row0 + ai * 128 + m * 16; const size_t off = (size_t)row * DM + col0; float q = 0.f;
; #pragma unroll
;                 for (int bj = 0; bj < 2; ++bj)
; #pragma unroll
;                     for (int n = 0; n < 2; ++n) { const size_t o = off + bj * 128 + n * 16; const f32x4 xv = *(const f32x4*)(xin + o) + acc[ai][bj][m][n]; *(f32x4*)(xout + o) = xv;
;                         q += (xv[0] * xv[0] + xv[1] * xv[1]) + (xv[2] * xv[2] + xv[3] * xv[3]);
;                         u32x2 w; w.x = cvt_pk_bf16(xv[0], xv[1]); w.y = cvt_pk_bf16(xv[2], xv[3]); *(u32x2*)(xb + o) = w; }
;                 q += __shfl_xor(q, 16); q += __shfl_xor(q, 32);
;                 if (fq == 0) ssq[(size_t)row * 16 + u.pn * 4 + wc] = q;
	v_pk_add_f32 v[200:201], v[32:33], v[200:201]
	v_pk_add_f32 v[198:199], v[30:31], v[198:199]
	global_store_dwordx4 v174, v[198:201], s[84:85]
	v_mul_f32_e32 v178, v201, v201
	v_mul_f32_e32 v177, v199, v199
	v_fmac_f32_e32 v177, v198, v198
	v_fmac_f32_e32 v178, v200, v200
	v_cvt_pk_bf16_f32 v180, v198, v199
	v_cvt_pk_bf16_f32 v181, v200, v201
	v_add_f32_e32 v179, v177, v178
	global_store_dwordx2 v175, v[180:181], s[18:19]
	s_waitcnt vmcnt(26)
	v_pk_add_f32 v[204:205], v[28:29], v[204:205]
	v_pk_add_f32 v[202:203], v[26:27], v[202:203]
	global_store_dwordx4 v174, v[202:205], s[84:85] offset:64
	v_mul_f32_e32 v178, v205, v205
	v_mul_f32_e32 v177, v203, v203
	v_fmac_f32_e32 v177, v202, v202
	v_fmac_f32_e32 v178, v204, v204
	v_cvt_pk_bf16_f32 v182, v202, v203
	v_cvt_pk_bf16_f32 v183, v204, v205
	v_add_f32_e32 v177, v177, v178
	v_add_f32_e32 v179, v179, v177
	global_store_dwordx2 v175, v[182:183], s[18:19] offset:32
	s_waitcnt vmcnt(27)
	v_pk_add_f32 v[208:209], v[24:25], v[208:209]
	v_pk_add_f32 v[206:207], v[22:23], v[206:207]
	global_store_dwordx4 v174, v[206:209], s[84:85] offset:512
	v_mul_f32_e32 v178, v209, v209
	v_mul_f32_e32 v177, v207, v207
	v_fmac_f32_e32 v177, v206, v206
	v_fmac_f32_e32 v178, v208, v208
	v_cvt_pk_bf16_f32 v180, v206, v207
	v_cvt_pk_bf16_f32 v181, v208, v209
	v_add_f32_e32 v177, v177, v178
	v_add_f32_e32 v179, v179, v177
	global_store_dwordx2 v175, v[180:181], s[18:19] offset:256
	s_waitcnt vmcnt(28)
	v_pk_add_f32 v[212:213], v[20:21], v[212:213]
	v_pk_add_f32 v[210:211], v[18:19], v[210:211]
	global_store_dwordx4 v174, v[210:213], s[84:85] offset:576
	v_mul_f32_e32 v178, v213, v213
	v_mul_f32_e32 v177, v211, v211
	v_fmac_f32_e32 v177, v210, v210
	v_fmac_f32_e32 v178, v212, v212
	v_cvt_pk_bf16_f32 v182, v210, v211
	v_cvt_pk_bf16_f32 v183, v212, v213
	v_add_f32_e32 v177, v177, v178
	v_add_f32_e32 v179, v179, v177
	global_store_dwordx2 v175, v[182:183], s[18:19] offset:288
	ds_bpermute_b32 v177, v141, v179
	s_waitcnt lgkmcnt(0)
	v_add_f32_e32 v179, v179, v177
	ds_bpermute_b32 v178, v172, v179
	s_waitcnt lgkmcnt(0)
	v_add_f32_e32 v179, v179, v178
	s_and_saveexec_b64 s[52:53], s[4:5]
	global_store_dword v176, v179, s[14:15]
	s_mov_b64 exec, s[52:53]
	v_add_u32_e32 v174, 0xb0000, v138
	v_add_u32_e32 v175, 0x58000, v139
	v_add_u32_e32 v176, 0x2c00, v140
	s_waitcnt vmcnt(21)
	v_pk_add_f32 v[216:217], v[16:17], v[216:217]
	v_pk_add_f32 v[214:215], v[14:15], v[214:215]
	global_store_dwordx4 v174, v[214:217], s[84:85]
	v_mul_f32_e32 v178, v217, v217
	v_mul_f32_e32 v177, v215, v215
	v_fmac_f32_e32 v177, v214, v214
	v_fmac_f32_e32 v178, v216, v216
	v_cvt_pk_bf16_f32 v180, v214, v215
	v_cvt_pk_bf16_f32 v181, v216, v217
	v_add_f32_e32 v179, v177, v178
	global_store_dwordx2 v175, v[180:181], s[18:19]
	s_waitcnt vmcnt(22)
	v_pk_add_f32 v[220:221], v[12:13], v[220:221]
	v_pk_add_f32 v[218:219], v[10:11], v[218:219]
	global_store_dwordx4 v174, v[218:221], s[84:85] offset:64
	v_mul_f32_e32 v178, v221, v221
	v_mul_f32_e32 v177, v219, v219
	v_fmac_f32_e32 v177, v218, v218
	v_fmac_f32_e32 v178, v220, v220
	v_cvt_pk_bf16_f32 v182, v218, v219
	v_cvt_pk_bf16_f32 v183, v220, v221
	v_add_f32_e32 v177, v177, v178
	v_add_f32_e32 v179, v179, v177
	global_store_dwordx2 v175, v[182:183], s[18:19] offset:32
	s_waitcnt vmcnt(23)
	v_pk_add_f32 v[224:225], v[8:9], v[224:225]
	v_pk_add_f32 v[222:223], v[6:7], v[222:223]
	global_store_dwordx4 v174, v[222:225], s[84:85] offset:512
	v_mul_f32_e32 v178, v225, v225
	v_mul_f32_e32 v177, v223, v223
	v_fmac_f32_e32 v177, v222, v222
	v_fmac_f32_e32 v178, v224, v224
	v_cvt_pk_bf16_f32 v180, v222, v223
	v_cvt_pk_bf16_f32 v181, v224, v225
	v_add_f32_e32 v177, v177, v178
	v_add_f32_e32 v179, v179, v177
	global_store_dwordx2 v175, v[180:181], s[18:19] offset:256
	s_waitcnt vmcnt(24)
	v_pk_add_f32 v[228:229], v[4:5], v[228:229]
	v_pk_add_f32 v[226:227], v[2:3], v[226:227]
	global_store_dwordx4 v174, v[226:229], s[84:85] offset:576
	v_mul_f32_e32 v178, v229, v229
	v_mul_f32_e32 v177, v227, v227
	v_fmac_f32_e32 v177, v226, v226
	v_fmac_f32_e32 v178, v228, v228
	v_cvt_pk_bf16_f32 v182, v226, v227
	v_cvt_pk_bf16_f32 v183, v228, v229
	v_add_f32_e32 v177, v177, v178
	v_add_f32_e32 v179, v179, v177
	global_store_dwordx2 v175, v[182:183], s[18:19] offset:288
	ds_bpermute_b32 v177, v141, v179
	s_waitcnt lgkmcnt(0)
	v_add_f32_e32 v179, v179, v177
	ds_bpermute_b32 v178, v172, v179
	s_waitcnt lgkmcnt(0)
	v_add_f32_e32 v179, v179, v178
	s_and_saveexec_b64 s[52:53], s[4:5]
	global_store_dword v176, v179, s[14:15]
	s_mov_b64 exec, s[52:53]
	s_and_b64 vcc, exec, s[6:7]
	s_mov_b64 s[6:7], -1
	s_cbranch_vccnz .LBB0_406
	s_andn2_b64 vcc, exec, s[16:17]
	s_cbranch_vccnz .LBB0_405
	s_barrier
	s_branch .LBB0_405
